# GEMM K loops: per-segment s_setprio flips deleted, one static priority raise for waves 4-7 before each K loop (reset after); attention-A gate loads at round start
# speedup vs baseline: 1.0161x; 1.0058x over previous
.LBB0_107:
	s_add_u32 s47, s8, 0x100
	s_addc_u32 s63, s9, 0
	v_lshl_add_u64 v[130:131], s[26:27], 0, v[150:151]
	v_lshl_add_u64 v[132:133], s[26:27], 0, v[156:157]
	s_mov_b32 s64, -2
	s_mov_b64 s[8:9], 0
	v_readfirstlane_b32 s98, v0
	s_nop 3
	s_lshr_b32 s98, s98, 8
	s_cmp_eq_u32 s98, 1
	s_cbranch_scc0 .Lprio_g1_done
	s_setprio 1
.Lprio_g1_done:
.LBB0_108:
	v_add_u32_e32 v146, s58, v172
	ds_read_b128 v[134:137], v146
	ds_read_b128 v[162:165], v146 offset:1024
	ds_read_b128 v[166:169], v146 offset:2048
	ds_read_b128 v[184:187], v146 offset:3072
	v_add_u32_e32 v146, s59, v172
	s_add_u32 s36, s26, s8
	ds_read_b128 v[188:191], v146
	ds_read_b128 v[192:195], v146 offset:1024
	ds_read_b128 v[196:199], v146 offset:2048
	ds_read_b128 v[200:203], v146 offset:3072
	s_addc_u32 s37, s27, s9
	s_add_u32 s36, s36, 0x100
	s_addc_u32 s37, s37, 0
	s_add_u32 s65, s47, s8
	s_addc_u32 s66, s63, s9
	s_cmpk_eq_i32 s8, 0x700
	s_cselect_b32 s39, s51, s37
	s_cselect_b32 s38, s50, s36
	s_cselect_b32 s37, s49, s66
	s_cselect_b32 s36, s48, s65
	v_lshl_add_u64 v[236:237], v[130:131], 0, s[8:9]
	s_add_i32 m0, s19, 0xc000
	ds_read_b128 v[204:207], v173
	ds_read_b128 v[208:211], v173 offset:1024
	ds_read_b128 v[212:215], v173 offset:2048
	ds_read_b128 v[216:219], v173 offset:3072
	ds_read_b128 v[220:223], v173 offset:4096
	ds_read_b128 v[224:227], v173 offset:5120
	ds_read_b128 v[228:231], v173 offset:6144
	ds_read_b128 v[232:235], v173 offset:7168
	global_load_lds_dwordx4 v[236:237], off
	v_lshl_add_u64 v[236:237], v[132:133], 0, s[8:9]
	s_add_i32 m0, s19, 0xe000
	s_nop 0
	global_load_lds_dwordx4 v[236:237], off
	s_waitcnt vmcnt(8)
	s_waitcnt lgkmcnt(0)
	s_barrier
	s_waitcnt lgkmcnt(0)
	v_mfma_f32_16x16x32_bf16 v[126:129], v[134:137], v[204:207], v[126:129]
	v_mfma_f32_16x16x32_bf16 v[122:125], v[166:169], v[204:207], v[122:125]
	v_mfma_f32_16x16x32_bf16 v[118:121], v[134:137], v[212:215], v[118:121]
	v_mfma_f32_16x16x32_bf16 v[114:117], v[166:169], v[212:215], v[114:117]
	v_mfma_f32_16x16x32_bf16 v[110:113], v[134:137], v[220:223], v[110:113]
	v_mfma_f32_16x16x32_bf16 v[106:109], v[166:169], v[220:223], v[106:109]
	v_mfma_f32_16x16x32_bf16 v[102:105], v[134:137], v[228:231], v[102:105]
	v_mfma_f32_16x16x32_bf16 v[98:101], v[166:169], v[228:231], v[98:101]
	v_mfma_f32_16x16x32_bf16 v[126:129], v[162:165], v[208:211], v[126:129]
	v_mfma_f32_16x16x32_bf16 v[122:125], v[184:187], v[208:211], v[122:125]
	v_mfma_f32_16x16x32_bf16 v[118:121], v[162:165], v[216:219], v[118:121]
	v_mfma_f32_16x16x32_bf16 v[114:117], v[184:187], v[216:219], v[114:117]
	v_mfma_f32_16x16x32_bf16 v[110:113], v[162:165], v[224:227], v[110:113]
	v_mfma_f32_16x16x32_bf16 v[106:109], v[184:187], v[224:227], v[106:109]
	v_mfma_f32_16x16x32_bf16 v[102:105], v[162:165], v[232:235], v[102:105]
	v_mfma_f32_16x16x32_bf16 v[98:101], v[184:187], v[232:235], v[98:101]
	v_mfma_f32_16x16x32_bf16 v[94:97], v[188:191], v[204:207], v[94:97]
	v_mfma_f32_16x16x32_bf16 v[90:93], v[196:199], v[204:207], v[90:93]
	v_mfma_f32_16x16x32_bf16 v[86:89], v[188:191], v[212:215], v[86:89]
	v_mfma_f32_16x16x32_bf16 v[82:85], v[196:199], v[212:215], v[82:85]
	v_mfma_f32_16x16x32_bf16 v[78:81], v[188:191], v[220:223], v[78:81]
	v_mfma_f32_16x16x32_bf16 v[74:77], v[196:199], v[220:223], v[74:77]
	v_mfma_f32_16x16x32_bf16 v[70:73], v[188:191], v[228:231], v[70:73]
	v_mfma_f32_16x16x32_bf16 v[66:69], v[196:199], v[228:231], v[66:69]
	v_mfma_f32_16x16x32_bf16 v[94:97], v[192:195], v[208:211], v[94:97]
	v_mfma_f32_16x16x32_bf16 v[90:93], v[200:203], v[208:211], v[90:93]
	v_mfma_f32_16x16x32_bf16 v[86:89], v[192:195], v[216:219], v[86:89]
	v_mfma_f32_16x16x32_bf16 v[82:85], v[200:203], v[216:219], v[82:85]
	v_mfma_f32_16x16x32_bf16 v[78:81], v[192:195], v[224:227], v[78:81]
	v_mfma_f32_16x16x32_bf16 v[74:77], v[200:203], v[224:227], v[74:77]
	v_mfma_f32_16x16x32_bf16 v[70:73], v[192:195], v[232:235], v[70:73]
	v_mfma_f32_16x16x32_bf16 v[66:69], v[200:203], v[232:235], v[66:69]
	s_barrier
	s_add_i32 s65, s58, s18
	v_lshl_add_u64 v[236:237], s[36:37], 0, v[138:139]
	s_mov_b32 m0, s65
	ds_read_b128 v[204:207], v173 offset:16384
	ds_read_b128 v[208:211], v173 offset:17408
	ds_read_b128 v[212:215], v173 offset:18432
	ds_read_b128 v[216:219], v173 offset:19456
	ds_read_b128 v[220:223], v173 offset:20480
	ds_read_b128 v[224:227], v173 offset:21504
	ds_read_b128 v[228:231], v173 offset:22528
	ds_read_b128 v[232:235], v173 offset:23552
	global_load_lds_dwordx4 v[236:237], off
	s_add_i32 m0, s65, 0x2000
	s_add_u32 s66, s36, 0x40000
	v_lshl_add_u64 v[238:239], s[36:37], 0, v[140:141]
	s_addc_u32 s67, s37, 0
	s_add_i32 s65, s59, s18
	global_load_lds_dwordx4 v[238:239], off
	v_lshl_add_u64 v[240:241], s[66:67], 0, v[138:139]
	s_mov_b32 m0, s65
	v_lshl_add_u64 v[242:243], s[38:39], 0, v[144:145]
	global_load_lds_dwordx4 v[240:241], off
	v_lshl_add_u64 v[240:241], s[66:67], 0, v[140:141]
	s_add_i32 m0, s65, 0x2000
	s_nop 0
	global_load_lds_dwordx4 v[240:241], off
	v_lshl_add_u64 v[240:241], s[38:39], 0, v[142:143]
	s_mov_b32 m0, s19
	s_nop 0
	global_load_lds_dwordx4 v[240:241], off
	s_mov_b32 m0, s24
	s_nop 0
	global_load_lds_dwordx4 v[242:243], off
	s_waitcnt vmcnt(8)
	s_waitcnt lgkmcnt(0)
	s_barrier
	s_waitcnt lgkmcnt(0)
	v_mfma_f32_16x16x32_bf16 v[62:65], v[134:137], v[204:207], v[62:65]
	v_mfma_f32_16x16x32_bf16 v[58:61], v[166:169], v[204:207], v[58:61]
	v_mfma_f32_16x16x32_bf16 v[54:57], v[134:137], v[212:215], v[54:57]
	v_mfma_f32_16x16x32_bf16 v[50:53], v[166:169], v[212:215], v[50:53]
	v_mfma_f32_16x16x32_bf16 v[46:49], v[134:137], v[220:223], v[46:49]
	v_mfma_f32_16x16x32_bf16 v[42:45], v[166:169], v[220:223], v[42:45]
	v_mfma_f32_16x16x32_bf16 v[38:41], v[134:137], v[228:231], v[38:41]
	v_mfma_f32_16x16x32_bf16 v[34:37], v[166:169], v[228:231], v[34:37]
	v_mfma_f32_16x16x32_bf16 v[62:65], v[162:165], v[208:211], v[62:65]
	v_mfma_f32_16x16x32_bf16 v[58:61], v[184:187], v[208:211], v[58:61]
	v_mfma_f32_16x16x32_bf16 v[54:57], v[162:165], v[216:219], v[54:57]
	v_mfma_f32_16x16x32_bf16 v[50:53], v[184:187], v[216:219], v[50:53]
	v_mfma_f32_16x16x32_bf16 v[46:49], v[162:165], v[224:227], v[46:49]
	v_mfma_f32_16x16x32_bf16 v[42:45], v[184:187], v[224:227], v[42:45]
	v_mfma_f32_16x16x32_bf16 v[38:41], v[162:165], v[232:235], v[38:41]
	v_mfma_f32_16x16x32_bf16 v[34:37], v[184:187], v[232:235], v[34:37]
	v_mfma_f32_16x16x32_bf16 v[30:33], v[188:191], v[204:207], v[30:33]
	v_mfma_f32_16x16x32_bf16 v[26:29], v[196:199], v[204:207], v[26:29]
	v_mfma_f32_16x16x32_bf16 v[22:25], v[188:191], v[212:215], v[22:25]
	v_mfma_f32_16x16x32_bf16 v[18:21], v[196:199], v[212:215], v[18:21]
	v_mfma_f32_16x16x32_bf16 v[14:17], v[188:191], v[220:223], v[14:17]
	v_mfma_f32_16x16x32_bf16 v[10:13], v[196:199], v[220:223], v[10:13]
	v_mfma_f32_16x16x32_bf16 v[6:9], v[188:191], v[228:231], v[6:9]
	v_mfma_f32_16x16x32_bf16 v[2:5], v[196:199], v[228:231], v[2:5]
	v_mfma_f32_16x16x32_bf16 v[30:33], v[192:195], v[208:211], v[30:33]
	v_mfma_f32_16x16x32_bf16 v[26:29], v[200:203], v[208:211], v[26:29]
	v_mfma_f32_16x16x32_bf16 v[22:25], v[192:195], v[216:219], v[22:25]
	v_mfma_f32_16x16x32_bf16 v[18:21], v[200:203], v[216:219], v[18:21]
	v_mfma_f32_16x16x32_bf16 v[14:17], v[192:195], v[224:227], v[14:17]
	v_mfma_f32_16x16x32_bf16 v[10:13], v[200:203], v[224:227], v[10:13]
	v_mfma_f32_16x16x32_bf16 v[6:9], v[192:195], v[232:235], v[6:9]
	v_mfma_f32_16x16x32_bf16 v[2:5], v[200:203], v[232:235], v[2:5]
	s_barrier
	s_add_i32 s65, 0, 0x18000
	v_add_u32_e32 v146, s65, v172
	s_add_i32 s66, 0, 0x1c000
	ds_read_b128 v[134:137], v146
	ds_read_b128 v[162:165], v146 offset:1024
	ds_read_b128 v[166:169], v146 offset:2048
	ds_read_b128 v[184:187], v146 offset:3072
	v_add_u32_e32 v146, s66, v172
	ds_read_b128 v[188:191], v146
	ds_read_b128 v[192:195], v146 offset:1024
	ds_read_b128 v[196:199], v146 offset:2048
	ds_read_b128 v[200:203], v146 offset:3072
	s_add_u32 s38, s38, 0x40000
	s_addc_u32 s39, s39, 0
	s_mov_b32 m0, s34
	v_lshl_add_u64 v[244:245], s[38:39], 0, v[142:143]
	ds_read_b128 v[204:207], v173 offset:32768
	ds_read_b128 v[208:211], v173 offset:33792
	ds_read_b128 v[212:215], v173 offset:34816
	ds_read_b128 v[216:219], v173 offset:35840
	ds_read_b128 v[220:223], v173 offset:36864
	ds_read_b128 v[224:227], v173 offset:37888
	ds_read_b128 v[228:231], v173 offset:38912
	ds_read_b128 v[232:235], v173 offset:39936
	global_load_lds_dwordx4 v[244:245], off
	v_lshl_add_u64 v[244:245], s[38:39], 0, v[144:145]
	s_mov_b32 m0, s35
	s_nop 0
	global_load_lds_dwordx4 v[244:245], off
	s_waitcnt vmcnt(8)
	s_waitcnt lgkmcnt(0)
	s_barrier
	s_waitcnt lgkmcnt(0)
	v_mfma_f32_16x16x32_bf16 v[126:129], v[134:137], v[204:207], v[126:129]
	v_mfma_f32_16x16x32_bf16 v[122:125], v[166:169], v[204:207], v[122:125]
	v_mfma_f32_16x16x32_bf16 v[118:121], v[134:137], v[212:215], v[118:121]
	v_mfma_f32_16x16x32_bf16 v[114:117], v[166:169], v[212:215], v[114:117]
	v_mfma_f32_16x16x32_bf16 v[110:113], v[134:137], v[220:223], v[110:113]
	v_mfma_f32_16x16x32_bf16 v[106:109], v[166:169], v[220:223], v[106:109]
	v_mfma_f32_16x16x32_bf16 v[102:105], v[134:137], v[228:231], v[102:105]
	v_mfma_f32_16x16x32_bf16 v[98:101], v[166:169], v[228:231], v[98:101]
	v_mfma_f32_16x16x32_bf16 v[126:129], v[162:165], v[208:211], v[126:129]
	v_mfma_f32_16x16x32_bf16 v[122:125], v[184:187], v[208:211], v[122:125]
	v_mfma_f32_16x16x32_bf16 v[118:121], v[162:165], v[216:219], v[118:121]
	v_mfma_f32_16x16x32_bf16 v[114:117], v[184:187], v[216:219], v[114:117]
	v_mfma_f32_16x16x32_bf16 v[110:113], v[162:165], v[224:227], v[110:113]
	v_mfma_f32_16x16x32_bf16 v[106:109], v[184:187], v[224:227], v[106:109]
	v_mfma_f32_16x16x32_bf16 v[102:105], v[162:165], v[232:235], v[102:105]
	v_mfma_f32_16x16x32_bf16 v[98:101], v[184:187], v[232:235], v[98:101]
	v_mfma_f32_16x16x32_bf16 v[94:97], v[188:191], v[204:207], v[94:97]
	v_mfma_f32_16x16x32_bf16 v[90:93], v[196:199], v[204:207], v[90:93]
	v_mfma_f32_16x16x32_bf16 v[86:89], v[188:191], v[212:215], v[86:89]
	v_mfma_f32_16x16x32_bf16 v[82:85], v[196:199], v[212:215], v[82:85]
	v_mfma_f32_16x16x32_bf16 v[78:81], v[188:191], v[220:223], v[78:81]
	v_mfma_f32_16x16x32_bf16 v[74:77], v[196:199], v[220:223], v[74:77]
	v_mfma_f32_16x16x32_bf16 v[70:73], v[188:191], v[228:231], v[70:73]
	v_mfma_f32_16x16x32_bf16 v[66:69], v[196:199], v[228:231], v[66:69]
	v_mfma_f32_16x16x32_bf16 v[94:97], v[192:195], v[208:211], v[94:97]
	v_mfma_f32_16x16x32_bf16 v[90:93], v[200:203], v[208:211], v[90:93]
	v_mfma_f32_16x16x32_bf16 v[86:89], v[192:195], v[216:219], v[86:89]
	v_mfma_f32_16x16x32_bf16 v[82:85], v[200:203], v[216:219], v[82:85]
	v_mfma_f32_16x16x32_bf16 v[78:81], v[192:195], v[224:227], v[78:81]
	v_mfma_f32_16x16x32_bf16 v[74:77], v[200:203], v[224:227], v[74:77]
	v_mfma_f32_16x16x32_bf16 v[70:73], v[192:195], v[232:235], v[70:73]
	v_mfma_f32_16x16x32_bf16 v[66:69], v[200:203], v[232:235], v[66:69]
	s_barrier
	s_add_i32 s38, s65, s18
	v_lshl_add_u64 v[236:237], v[236:237], 0, s[40:41]
	s_mov_b32 m0, s38
	ds_read_b128 v[204:207], v173 offset:49152
	ds_read_b128 v[208:211], v173 offset:50176
	ds_read_b128 v[212:215], v173 offset:51200
	ds_read_b128 v[216:219], v173 offset:52224
	ds_read_b128 v[220:223], v173 offset:53248
	ds_read_b128 v[224:227], v173 offset:54272
	ds_read_b128 v[228:231], v173 offset:55296
	ds_read_b128 v[232:235], v173 offset:56320
	global_load_lds_dwordx4 v[236:237], off
	s_add_i32 m0, s38, 0x2000
	s_add_u32 s36, s36, 0x40080
	v_lshl_add_u64 v[236:237], v[238:239], 0, s[40:41]
	s_addc_u32 s37, s37, 0
	s_add_i32 s38, s66, s18
	global_load_lds_dwordx4 v[236:237], off
	v_lshl_add_u64 v[236:237], s[36:37], 0, v[138:139]
	s_mov_b32 m0, s38
	s_nop 0
	global_load_lds_dwordx4 v[236:237], off
	v_lshl_add_u64 v[236:237], s[36:37], 0, v[140:141]
	s_add_i32 m0, s38, 0x2000
	s_nop 0
	global_load_lds_dwordx4 v[236:237], off
	v_lshl_add_u64 v[236:237], v[240:241], 0, s[40:41]
	s_mov_b32 m0, s55
	s_nop 0
	global_load_lds_dwordx4 v[236:237], off
	v_lshl_add_u64 v[236:237], v[242:243], 0, s[40:41]
	s_mov_b32 m0, s56
	s_nop 0
	global_load_lds_dwordx4 v[236:237], off
	s_waitcnt vmcnt(8)
	s_waitcnt lgkmcnt(0)
	s_barrier
	s_waitcnt lgkmcnt(0)
	v_mfma_f32_16x16x32_bf16 v[62:65], v[134:137], v[204:207], v[62:65]
	v_mfma_f32_16x16x32_bf16 v[58:61], v[166:169], v[204:207], v[58:61]
	v_mfma_f32_16x16x32_bf16 v[54:57], v[134:137], v[212:215], v[54:57]
	v_mfma_f32_16x16x32_bf16 v[50:53], v[166:169], v[212:215], v[50:53]
	v_mfma_f32_16x16x32_bf16 v[46:49], v[134:137], v[220:223], v[46:49]
	v_mfma_f32_16x16x32_bf16 v[42:45], v[166:169], v[220:223], v[42:45]
	v_mfma_f32_16x16x32_bf16 v[38:41], v[134:137], v[228:231], v[38:41]
	v_mfma_f32_16x16x32_bf16 v[34:37], v[166:169], v[228:231], v[34:37]
	v_mfma_f32_16x16x32_bf16 v[62:65], v[162:165], v[208:211], v[62:65]
	v_mfma_f32_16x16x32_bf16 v[58:61], v[184:187], v[208:211], v[58:61]
	v_mfma_f32_16x16x32_bf16 v[54:57], v[162:165], v[216:219], v[54:57]
	v_mfma_f32_16x16x32_bf16 v[50:53], v[184:187], v[216:219], v[50:53]
	v_mfma_f32_16x16x32_bf16 v[46:49], v[162:165], v[224:227], v[46:49]
	v_mfma_f32_16x16x32_bf16 v[42:45], v[184:187], v[224:227], v[42:45]
	v_mfma_f32_16x16x32_bf16 v[38:41], v[162:165], v[232:235], v[38:41]
	v_mfma_f32_16x16x32_bf16 v[34:37], v[184:187], v[232:235], v[34:37]
	v_mfma_f32_16x16x32_bf16 v[30:33], v[188:191], v[204:207], v[30:33]
	v_mfma_f32_16x16x32_bf16 v[26:29], v[196:199], v[204:207], v[26:29]
	v_mfma_f32_16x16x32_bf16 v[22:25], v[188:191], v[212:215], v[22:25]
	v_mfma_f32_16x16x32_bf16 v[18:21], v[196:199], v[212:215], v[18:21]
	v_mfma_f32_16x16x32_bf16 v[14:17], v[188:191], v[220:223], v[14:17]
	v_mfma_f32_16x16x32_bf16 v[10:13], v[196:199], v[220:223], v[10:13]
	v_mfma_f32_16x16x32_bf16 v[6:9], v[188:191], v[228:231], v[6:9]
	v_mfma_f32_16x16x32_bf16 v[2:5], v[196:199], v[228:231], v[2:5]
	v_mfma_f32_16x16x32_bf16 v[30:33], v[192:195], v[208:211], v[30:33]
	v_mfma_f32_16x16x32_bf16 v[26:29], v[200:203], v[208:211], v[26:29]
	v_mfma_f32_16x16x32_bf16 v[22:25], v[192:195], v[216:219], v[22:25]
	v_mfma_f32_16x16x32_bf16 v[18:21], v[200:203], v[216:219], v[18:21]
	v_mfma_f32_16x16x32_bf16 v[14:17], v[192:195], v[224:227], v[14:17]
	v_mfma_f32_16x16x32_bf16 v[10:13], v[200:203], v[224:227], v[10:13]
	v_mfma_f32_16x16x32_bf16 v[6:9], v[192:195], v[232:235], v[6:9]
	v_mfma_f32_16x16x32_bf16 v[2:5], v[200:203], v[232:235], v[2:5]
	s_barrier
	s_add_i32 s64, s64, 2
	s_add_u32 s8, s8, 0x100
	s_addc_u32 s9, s9, 0
	s_cmp_gt_u32 s64, 13
	s_cbranch_scc0 .LBB0_108
	s_setprio 0
	s_and_b64 vcc, exec, s[42:43]
	s_cbranch_vccz .LBB0_111
	s_barrier

.La0_round:
	v_mov_b32_e32 v88, 0xf149f2ca
	v_mov_b32_e32 v72, 0
	v_mov_b32_e32 v73, 0
	v_mov_b32_e32 v74, 0
	v_mov_b32_e32 v75, 0
	v_mov_b32_e32 v8, 0
	v_mov_b32_e32 v9, 0
	v_mov_b32_e32 v10, 0
	v_mov_b32_e32 v11, 0
	v_mov_b32_e32 v12, 0
	v_mov_b32_e32 v13, 0
	v_mov_b32_e32 v14, 0
	v_mov_b32_e32 v15, 0
	v_mov_b32_e32 v16, 0
	v_mov_b32_e32 v17, 0
	v_mov_b32_e32 v18, 0
	v_mov_b32_e32 v19, 0
	v_mov_b32_e32 v20, 0
	v_mov_b32_e32 v21, 0
	v_mov_b32_e32 v22, 0
	v_mov_b32_e32 v23, 0
	v_mov_b32_e32 v89, 0xf149f2ca
	v_mov_b32_e32 v76, 0
	v_mov_b32_e32 v77, 0
	v_mov_b32_e32 v78, 0
	v_mov_b32_e32 v79, 0
	v_mov_b32_e32 v24, 0
	v_mov_b32_e32 v25, 0
	v_mov_b32_e32 v26, 0
	v_mov_b32_e32 v27, 0
	v_mov_b32_e32 v28, 0
	v_mov_b32_e32 v29, 0
	v_mov_b32_e32 v30, 0
	v_mov_b32_e32 v31, 0
	v_mov_b32_e32 v32, 0
	v_mov_b32_e32 v33, 0
	v_mov_b32_e32 v34, 0
	v_mov_b32_e32 v35, 0
	v_mov_b32_e32 v36, 0
	v_mov_b32_e32 v37, 0
	v_mov_b32_e32 v38, 0
	v_mov_b32_e32 v39, 0
	v_mov_b32_e32 v90, 0xf149f2ca
	v_mov_b32_e32 v80, 0
	v_mov_b32_e32 v81, 0
	v_mov_b32_e32 v82, 0
	v_mov_b32_e32 v83, 0
	v_mov_b32_e32 v40, 0
	v_mov_b32_e32 v41, 0
	v_mov_b32_e32 v42, 0
	v_mov_b32_e32 v43, 0
	v_mov_b32_e32 v44, 0
	v_mov_b32_e32 v45, 0
	v_mov_b32_e32 v46, 0
	v_mov_b32_e32 v47, 0
	v_mov_b32_e32 v48, 0
	v_mov_b32_e32 v49, 0
	v_mov_b32_e32 v50, 0
	v_mov_b32_e32 v51, 0
	v_mov_b32_e32 v52, 0
	v_mov_b32_e32 v53, 0
	v_mov_b32_e32 v54, 0
	v_mov_b32_e32 v55, 0
	v_mov_b32_e32 v91, 0xf149f2ca
	v_mov_b32_e32 v84, 0
	v_mov_b32_e32 v85, 0
	v_mov_b32_e32 v86, 0
	v_mov_b32_e32 v87, 0
	v_mov_b32_e32 v56, 0
	v_mov_b32_e32 v57, 0
	v_mov_b32_e32 v58, 0
	v_mov_b32_e32 v59, 0
	v_mov_b32_e32 v60, 0
	v_mov_b32_e32 v61, 0
	v_mov_b32_e32 v62, 0
	v_mov_b32_e32 v63, 0
	v_mov_b32_e32 v64, 0
	v_mov_b32_e32 v65, 0
	v_mov_b32_e32 v66, 0
	v_mov_b32_e32 v67, 0
	v_mov_b32_e32 v68, 0
	v_mov_b32_e32 v69, 0
	v_mov_b32_e32 v70, 0
	v_mov_b32_e32 v71, 0
	s_mov_b32 s44, 0
	s_mov_b64 s[100:101], 0
	s_sub_i32 s5, s47, s42
	s_lshl_b32 s5, s5, 2
	s_mov_b32 s0, 0x11111111
	s_mov_b32 s1, 0
	s_lshl_b64 s[0:1], s[0:1], s5
	s_or_b64 s[100:101], s[100:101], s[0:1]
	s_sub_i32 s5, s48, s42
	s_lshl_b32 s5, s5, 2
	s_add_i32 s5, s5, 1
	s_mov_b32 s0, 0x11111111
	s_mov_b32 s1, 0
	s_lshl_b64 s[0:1], s[0:1], s5
	s_or_b64 s[100:101], s[100:101], s[0:1]
	s_sub_i32 s5, s49, s42
	s_lshl_b32 s5, s5, 2
	s_add_i32 s5, s5, 2
	s_mov_b32 s0, 0x11111111
	s_mov_b32 s1, 0
	s_lshl_b64 s[0:1], s[0:1], s5
	s_or_b64 s[100:101], s[100:101], s[0:1]
	s_sub_i32 s5, s50, s42
	s_lshl_b32 s5, s5, 2
	s_add_i32 s5, s5, 3
	s_mov_b32 s0, 0x11111111
	s_mov_b32 s1, 0
	s_lshl_b64 s[0:1], s[0:1], s5
	s_or_b64 s[100:101], s[100:101], s[0:1]
	s_add_i32 s5, s41, s54
	s_add_i32 s5, s5, 0
	s_lshl_b32 s5, s5, 17
	s_add_u32 s0, s56, s5
	s_addc_u32 s1, s57, 0
	global_load_dwordx4 v[210:213], v196, s[0:1] nt
	global_load_dwordx4 v[214:217], v196, s[0:1] offset:16 nt
	s_add_i32 s5, s41, s54
	s_add_i32 s5, s5, 2
	s_lshl_b32 s5, s5, 17
	s_add_u32 s0, s56, s5
	s_addc_u32 s1, s57, 0
	global_load_dwordx4 v[218:221], v196, s[0:1] nt
	global_load_dwordx4 v[222:225], v196, s[0:1] offset:16 nt
	s_waitcnt vmcnt(4) lgkmcnt(0)
	s_barrier
	s_branch .La0_ss_in

.La0_ss_in:
	s_lshl_b32 s60, s44, 1
	s_add_i32 s60, s60, s42
	s_lshl_b32 s5, s44, 3
	s_lshr_b64 s[0:1], s[100:101], s5
	s_and_b32 s64, s0, 15
	s_bfe_u32 s32, s0, 0x40004
	s_and_b32 s61, s62, 1
	s_lshl_b32 s61, s61, 15
	s_cmp_eq_u32 s64, 0
	s_cbranch_scc1 .La0_noread0
	v_add_u32_e32 v207, s61, v188
	v_add_u32_e32 v208, s61, v189
	v_add_u32_e32 v209, s61, v190
	ds_read_b128 v[124:127], v207
	ds_read_b128 v[132:135], v207 offset:512
	ds_read_b128 v[128:131], v208
	ds_read_b128 v[136:139], v208 offset:512
	ds_read_b128 v[140:143], v209 offset:0
	ds_read_b128 v[144:147], v209 offset:512
	ds_read_b128 v[148:151], v209 offset:1024
	ds_read_b128 v[152:155], v209 offset:1536
	s_sub_i32 s0, s60, s41
	s_sub_i32 s0, s0, s54
	s_add_i32 s0, s0, 1
	s_lshl_b32 s0, s0, 11
	v_add_u32_e32 v167, s0, v250
	ds_read_b128 v[156:159], v167 offset:12288
	ds_read_b128 v[160:163], v167 offset:13312
	ds_read_b128 v[232:235], v167 offset:8192
	ds_read_b128 v[236:239], v167 offset:9216
	ds_read_b128 v[180:183], v167 offset:4096
	ds_read_b128 v[184:187], v167 offset:5120
	ds_read_b128 v[198:201], v167 offset:0
	ds_read_b128 v[202:205], v167 offset:1024

.La0_noread1:
	s_lshl_b32 s60, s44, 1
	s_add_i32 s60, s60, s42
	s_cmp_eq_u32 s64, 0
	s_cbranch_scc1 .La0_rowdone_a
	s_cmp_eq_u32 s64, 15
	s_cbranch_scc1 .La0_pa_15
	s_cmp_eq_u32 s64, 7
	s_cbranch_scc1 .La0_pa_7
	s_cmp_eq_u32 s64, 14
	s_cbranch_scc1 .La0_pa_14
	s_cmp_eq_u32 s64, 3
	s_cbranch_scc1 .La0_pa_3
	s_cmp_eq_u32 s64, 12
	s_cbranch_scc1 .La0_pa_12
	s_cmp_eq_u32 s64, 1
	s_cbranch_scc1 .La0_pa_1
	s_cmp_eq_u32 s64, 8
	s_cbranch_scc1 .La0_pa_8
	s_branch .La0_rowdone_a
.La0_pa_15:
	s_waitcnt lgkmcnt(0)
	v_mfma_f32_16x16x32_bf16 v[156:159], v[124:127], v[92:95], v[156:159]
	v_mfma_f32_16x16x32_bf16 v[160:163], v[132:135], v[92:95], v[160:163]
	v_mfma_f32_16x16x32_bf16 v[156:159], v[128:131], v[96:99], v[156:159]
	v_mfma_f32_16x16x32_bf16 v[160:163], v[136:139], v[96:99], v[160:163]
	v_mfma_f32_16x16x32_bf16 v[232:235], v[124:127], v[100:103], v[232:235]
	v_mfma_f32_16x16x32_bf16 v[236:239], v[132:135], v[100:103], v[236:239]
	v_mfma_f32_16x16x32_bf16 v[232:235], v[128:131], v[104:107], v[232:235]
	v_mfma_f32_16x16x32_bf16 v[236:239], v[136:139], v[104:107], v[236:239]
	v_add_f32_e32 v164, 0x41000000, v88
	s_nop 3
	v_max3_f32 v165, v156, v157, v158
	v_max3_f32 v166, v159, v160, v161
	v_max3_f32 v165, v165, v162, v163
	v_max_f32_e32 v165, v165, v166
	v_cmp_gt_f32_e32 vcc, v165, v164
	s_cbranch_vccz .La0_nr_a15_0
	ds_bpermute_b32 v166, v194, v165
	s_waitcnt lgkmcnt(0)
	v_max_f32_e32 v165, v165, v166
	ds_bpermute_b32 v166, v195, v165
	s_waitcnt lgkmcnt(0)
	v_max3_f32 v165, v165, v166, v88
	v_sub_f32_e32 v166, v88, v165
	v_exp_f32_e32 v166, v166
	v_mov_b32_e32 v88, v165
	s_nop 0
	v_mul_f32_e32 v72, v72, v166
	v_mul_f32_e32 v73, v73, v166
	v_mul_f32_e32 v74, v74, v166
	v_mul_f32_e32 v75, v75, v166
	v_mul_f32_e32 v8, v8, v166
	v_mul_f32_e32 v9, v9, v166
	v_mul_f32_e32 v10, v10, v166
	v_mul_f32_e32 v11, v11, v166
	v_mul_f32_e32 v12, v12, v166
	v_mul_f32_e32 v13, v13, v166
	v_mul_f32_e32 v14, v14, v166
	v_mul_f32_e32 v15, v15, v166
	v_mul_f32_e32 v16, v16, v166
	v_mul_f32_e32 v17, v17, v166
	v_mul_f32_e32 v18, v18, v166
	v_mul_f32_e32 v19, v19, v166
	v_mul_f32_e32 v20, v20, v166
	v_mul_f32_e32 v21, v21, v166
	v_mul_f32_e32 v22, v22, v166
	v_mul_f32_e32 v23, v23, v166
.La0_nr_a15_0:
	v_sub_f32_e32 v156, v156, v88
	v_sub_f32_e32 v157, v157, v88
	v_sub_f32_e32 v158, v158, v88
	v_sub_f32_e32 v159, v159, v88
	v_sub_f32_e32 v160, v160, v88
	v_sub_f32_e32 v161, v161, v88
	v_sub_f32_e32 v162, v162, v88
	v_sub_f32_e32 v163, v163, v88
	v_exp_f32_e32 v156, v156
	v_exp_f32_e32 v157, v157
	v_exp_f32_e32 v158, v158
	v_exp_f32_e32 v159, v159
	v_exp_f32_e32 v160, v160
	v_exp_f32_e32 v161, v161
	v_exp_f32_e32 v162, v162
	v_exp_f32_e32 v163, v163
	s_nop 0
	v_cvt_pk_bf16_f32 v156, v156, v157
	v_cvt_pk_bf16_f32 v157, v158, v159
	v_cvt_pk_bf16_f32 v158, v160, v161
	v_cvt_pk_bf16_f32 v159, v162, v163
	v_mfma_f32_16x16x32_bf16 v[180:183], v[124:127], v[108:111], v[180:183]
	v_add_f32_e32 v240, 0x41000000, v89
	v_max3_f32 v241, v232, v233, v234
	v_mfma_f32_16x16x32_bf16 v[184:187], v[132:135], v[108:111], v[184:187]
	v_max3_f32 v242, v235, v236, v237
	v_max3_f32 v241, v241, v238, v239
	v_mfma_f32_16x16x32_bf16 v[180:183], v[128:131], v[112:115], v[180:183]
	v_max_f32_e32 v241, v241, v242
	v_cmp_gt_f32_e32 vcc, v241, v240
	v_mfma_f32_16x16x32_bf16 v[184:187], v[136:139], v[112:115], v[184:187]
	s_cbranch_vccz .La0_nr_a15_1
	ds_bpermute_b32 v242, v194, v241
	s_waitcnt lgkmcnt(0)
	v_max_f32_e32 v241, v241, v242
	ds_bpermute_b32 v242, v195, v241
	s_waitcnt lgkmcnt(0)
	v_max3_f32 v241, v241, v242, v89
	v_sub_f32_e32 v242, v89, v241
	v_exp_f32_e32 v242, v242
	v_mov_b32_e32 v89, v241
	s_nop 0
	v_mul_f32_e32 v76, v76, v242
	v_mul_f32_e32 v77, v77, v242
	v_mul_f32_e32 v78, v78, v242
	v_mul_f32_e32 v79, v79, v242
	v_mul_f32_e32 v24, v24, v242
	v_mul_f32_e32 v25, v25, v242
	v_mul_f32_e32 v26, v26, v242
	v_mul_f32_e32 v27, v27, v242
	v_mul_f32_e32 v28, v28, v242
	v_mul_f32_e32 v29, v29, v242
	v_mul_f32_e32 v30, v30, v242
	v_mul_f32_e32 v31, v31, v242
	v_mul_f32_e32 v32, v32, v242
	v_mul_f32_e32 v33, v33, v242
	v_mul_f32_e32 v34, v34, v242
	v_mul_f32_e32 v35, v35, v242
	v_mul_f32_e32 v36, v36, v242
	v_mul_f32_e32 v37, v37, v242
	v_mul_f32_e32 v38, v38, v242
	v_mul_f32_e32 v39, v39, v242
.La0_nr_a15_1:
	v_mfma_f32_16x16x32_bf16 v[8:11], v[140:143], v[156:159], v[8:11]
	v_sub_f32_e32 v232, v232, v89
	v_sub_f32_e32 v233, v233, v89
	v_sub_f32_e32 v234, v234, v89
	v_sub_f32_e32 v235, v235, v89
	v_mfma_f32_16x16x32_bf16 v[12:15], v[144:147], v[156:159], v[12:15]
	v_sub_f32_e32 v236, v236, v89
	v_sub_f32_e32 v237, v237, v89
	v_sub_f32_e32 v238, v238, v89
	v_sub_f32_e32 v239, v239, v89
	v_mfma_f32_16x16x32_bf16 v[16:19], v[148:151], v[156:159], v[16:19]
	v_exp_f32_e32 v232, v232
	v_exp_f32_e32 v233, v233
	v_exp_f32_e32 v234, v234
	v_exp_f32_e32 v235, v235
	v_mfma_f32_16x16x32_bf16 v[20:23], v[152:155], v[156:159], v[20:23]
	v_exp_f32_e32 v236, v236
	v_exp_f32_e32 v237, v237
	v_exp_f32_e32 v238, v238
	v_exp_f32_e32 v239, v239
	v_mfma_f32_16x16x32_bf16 v[72:75], v[176:179], v[156:159], v[72:75]
	s_nop 0
	v_cvt_pk_bf16_f32 v232, v232, v233
	v_cvt_pk_bf16_f32 v233, v234, v235
	v_cvt_pk_bf16_f32 v234, v236, v237
	v_cvt_pk_bf16_f32 v235, v238, v239
	v_mfma_f32_16x16x32_bf16 v[198:201], v[124:127], v[116:119], v[198:201]
	v_add_f32_e32 v1, 0x41000000, v90
	v_max3_f32 v3, v180, v181, v182
	v_mfma_f32_16x16x32_bf16 v[202:205], v[132:135], v[116:119], v[202:205]
	v_max3_f32 v4, v183, v184, v185
	v_max3_f32 v3, v3, v186, v187
	v_mfma_f32_16x16x32_bf16 v[198:201], v[128:131], v[120:123], v[198:201]
	v_max_f32_e32 v3, v3, v4
	v_cmp_gt_f32_e32 vcc, v3, v1
	v_mfma_f32_16x16x32_bf16 v[202:205], v[136:139], v[120:123], v[202:205]
	s_cbranch_vccz .La0_nr_a15_2
	ds_bpermute_b32 v4, v194, v3
	s_waitcnt lgkmcnt(0)
	v_max_f32_e32 v3, v3, v4
	ds_bpermute_b32 v4, v195, v3
	s_waitcnt lgkmcnt(0)
	v_max3_f32 v3, v3, v4, v90
	v_sub_f32_e32 v4, v90, v3
	v_exp_f32_e32 v4, v4
	v_mov_b32_e32 v90, v3
	s_nop 0
	v_mul_f32_e32 v80, v80, v4
	v_mul_f32_e32 v81, v81, v4
	v_mul_f32_e32 v82, v82, v4
	v_mul_f32_e32 v83, v83, v4
	v_mul_f32_e32 v40, v40, v4
	v_mul_f32_e32 v41, v41, v4
	v_mul_f32_e32 v42, v42, v4
	v_mul_f32_e32 v43, v43, v4
	v_mul_f32_e32 v44, v44, v4
	v_mul_f32_e32 v45, v45, v4
	v_mul_f32_e32 v46, v46, v4
	v_mul_f32_e32 v47, v47, v4
	v_mul_f32_e32 v48, v48, v4
	v_mul_f32_e32 v49, v49, v4
	v_mul_f32_e32 v50, v50, v4
	v_mul_f32_e32 v51, v51, v4
	v_mul_f32_e32 v52, v52, v4
	v_mul_f32_e32 v53, v53, v4
	v_mul_f32_e32 v54, v54, v4
	v_mul_f32_e32 v55, v55, v4

.La0_pa_14:
	s_waitcnt lgkmcnt(0)
	v_mfma_f32_16x16x32_bf16 v[232:235], v[124:127], v[100:103], v[232:235]
	v_mfma_f32_16x16x32_bf16 v[236:239], v[132:135], v[100:103], v[236:239]
	v_mfma_f32_16x16x32_bf16 v[232:235], v[128:131], v[104:107], v[232:235]
	v_mfma_f32_16x16x32_bf16 v[236:239], v[136:139], v[104:107], v[236:239]
	v_mfma_f32_16x16x32_bf16 v[180:183], v[124:127], v[108:111], v[180:183]
	v_mfma_f32_16x16x32_bf16 v[184:187], v[132:135], v[108:111], v[184:187]
	v_mfma_f32_16x16x32_bf16 v[180:183], v[128:131], v[112:115], v[180:183]
	v_mfma_f32_16x16x32_bf16 v[184:187], v[136:139], v[112:115], v[184:187]
	v_add_f32_e32 v240, 0x41000000, v89
	s_nop 3
	v_max3_f32 v241, v232, v233, v234
	v_max3_f32 v242, v235, v236, v237
	v_max3_f32 v241, v241, v238, v239
	v_max_f32_e32 v241, v241, v242
	v_cmp_gt_f32_e32 vcc, v241, v240
	s_cbranch_vccz .La0_nr_a14_1
	ds_bpermute_b32 v242, v194, v241
	s_waitcnt lgkmcnt(0)
	v_max_f32_e32 v241, v241, v242
	ds_bpermute_b32 v242, v195, v241
	s_waitcnt lgkmcnt(0)
	v_max3_f32 v241, v241, v242, v89
	v_sub_f32_e32 v242, v89, v241
	v_exp_f32_e32 v242, v242
	v_mov_b32_e32 v89, v241
	s_nop 0
	v_mul_f32_e32 v76, v76, v242
	v_mul_f32_e32 v77, v77, v242
	v_mul_f32_e32 v78, v78, v242
	v_mul_f32_e32 v79, v79, v242
	v_mul_f32_e32 v24, v24, v242
	v_mul_f32_e32 v25, v25, v242
	v_mul_f32_e32 v26, v26, v242
	v_mul_f32_e32 v27, v27, v242
	v_mul_f32_e32 v28, v28, v242
	v_mul_f32_e32 v29, v29, v242
	v_mul_f32_e32 v30, v30, v242
	v_mul_f32_e32 v31, v31, v242
	v_mul_f32_e32 v32, v32, v242
	v_mul_f32_e32 v33, v33, v242
	v_mul_f32_e32 v34, v34, v242
	v_mul_f32_e32 v35, v35, v242
	v_mul_f32_e32 v36, v36, v242
	v_mul_f32_e32 v37, v37, v242
	v_mul_f32_e32 v38, v38, v242
	v_mul_f32_e32 v39, v39, v242
.La0_nr_a14_1:
	v_sub_f32_e32 v232, v232, v89
	v_sub_f32_e32 v233, v233, v89
	v_sub_f32_e32 v234, v234, v89
	v_sub_f32_e32 v235, v235, v89
	v_sub_f32_e32 v236, v236, v89
	v_sub_f32_e32 v237, v237, v89
	v_sub_f32_e32 v238, v238, v89
	v_sub_f32_e32 v239, v239, v89
	v_exp_f32_e32 v232, v232
	v_exp_f32_e32 v233, v233
	v_exp_f32_e32 v234, v234
	v_exp_f32_e32 v235, v235
	v_exp_f32_e32 v236, v236
	v_exp_f32_e32 v237, v237
	v_exp_f32_e32 v238, v238
	v_exp_f32_e32 v239, v239
	s_nop 0
	v_cvt_pk_bf16_f32 v232, v232, v233
	v_cvt_pk_bf16_f32 v233, v234, v235
	v_cvt_pk_bf16_f32 v234, v236, v237
	v_cvt_pk_bf16_f32 v235, v238, v239
	v_mfma_f32_16x16x32_bf16 v[198:201], v[124:127], v[116:119], v[198:201]
	v_add_f32_e32 v1, 0x41000000, v90
	v_max3_f32 v3, v180, v181, v182
	v_mfma_f32_16x16x32_bf16 v[202:205], v[132:135], v[116:119], v[202:205]
	v_max3_f32 v4, v183, v184, v185
	v_max3_f32 v3, v3, v186, v187
	v_mfma_f32_16x16x32_bf16 v[198:201], v[128:131], v[120:123], v[198:201]
	v_max_f32_e32 v3, v3, v4
	v_cmp_gt_f32_e32 vcc, v3, v1
	v_mfma_f32_16x16x32_bf16 v[202:205], v[136:139], v[120:123], v[202:205]
	s_cbranch_vccz .La0_nr_a14_2
	ds_bpermute_b32 v4, v194, v3
	s_waitcnt lgkmcnt(0)
	v_max_f32_e32 v3, v3, v4
	ds_bpermute_b32 v4, v195, v3
	s_waitcnt lgkmcnt(0)
	v_max3_f32 v3, v3, v4, v90
	v_sub_f32_e32 v4, v90, v3
	v_exp_f32_e32 v4, v4
	v_mov_b32_e32 v90, v3
	s_nop 0
	v_mul_f32_e32 v80, v80, v4
	v_mul_f32_e32 v81, v81, v4
	v_mul_f32_e32 v82, v82, v4
	v_mul_f32_e32 v83, v83, v4
	v_mul_f32_e32 v40, v40, v4
	v_mul_f32_e32 v41, v41, v4
	v_mul_f32_e32 v42, v42, v4
	v_mul_f32_e32 v43, v43, v4
	v_mul_f32_e32 v44, v44, v4
	v_mul_f32_e32 v45, v45, v4
	v_mul_f32_e32 v46, v46, v4
	v_mul_f32_e32 v47, v47, v4
	v_mul_f32_e32 v48, v48, v4
	v_mul_f32_e32 v49, v49, v4
	v_mul_f32_e32 v50, v50, v4
	v_mul_f32_e32 v51, v51, v4
	v_mul_f32_e32 v52, v52, v4
	v_mul_f32_e32 v53, v53, v4
	v_mul_f32_e32 v54, v54, v4
	v_mul_f32_e32 v55, v55, v4

.La0_pa_12:
	s_waitcnt lgkmcnt(0)
	v_mfma_f32_16x16x32_bf16 v[180:183], v[124:127], v[108:111], v[180:183]
	v_mfma_f32_16x16x32_bf16 v[184:187], v[132:135], v[108:111], v[184:187]
	v_mfma_f32_16x16x32_bf16 v[180:183], v[128:131], v[112:115], v[180:183]
	v_mfma_f32_16x16x32_bf16 v[184:187], v[136:139], v[112:115], v[184:187]
	v_mfma_f32_16x16x32_bf16 v[198:201], v[124:127], v[116:119], v[198:201]
	v_mfma_f32_16x16x32_bf16 v[202:205], v[132:135], v[116:119], v[202:205]
	v_mfma_f32_16x16x32_bf16 v[198:201], v[128:131], v[120:123], v[198:201]
	v_mfma_f32_16x16x32_bf16 v[202:205], v[136:139], v[120:123], v[202:205]
	v_add_f32_e32 v1, 0x41000000, v90
	s_nop 3
	v_max3_f32 v3, v180, v181, v182
	v_max3_f32 v4, v183, v184, v185
	v_max3_f32 v3, v3, v186, v187
	v_max_f32_e32 v3, v3, v4
	v_cmp_gt_f32_e32 vcc, v3, v1
	s_cbranch_vccz .La0_nr_a12_2
	ds_bpermute_b32 v4, v194, v3
	s_waitcnt lgkmcnt(0)
	v_max_f32_e32 v3, v3, v4
	ds_bpermute_b32 v4, v195, v3
	s_waitcnt lgkmcnt(0)
	v_max3_f32 v3, v3, v4, v90
	v_sub_f32_e32 v4, v90, v3
	v_exp_f32_e32 v4, v4
	v_mov_b32_e32 v90, v3
	s_nop 0
	v_mul_f32_e32 v80, v80, v4
	v_mul_f32_e32 v81, v81, v4
	v_mul_f32_e32 v82, v82, v4
	v_mul_f32_e32 v83, v83, v4
	v_mul_f32_e32 v40, v40, v4
	v_mul_f32_e32 v41, v41, v4
	v_mul_f32_e32 v42, v42, v4
	v_mul_f32_e32 v43, v43, v4
	v_mul_f32_e32 v44, v44, v4
	v_mul_f32_e32 v45, v45, v4
	v_mul_f32_e32 v46, v46, v4
	v_mul_f32_e32 v47, v47, v4
	v_mul_f32_e32 v48, v48, v4
	v_mul_f32_e32 v49, v49, v4
	v_mul_f32_e32 v50, v50, v4
	v_mul_f32_e32 v51, v51, v4
	v_mul_f32_e32 v52, v52, v4
	v_mul_f32_e32 v53, v53, v4
	v_mul_f32_e32 v54, v54, v4
	v_mul_f32_e32 v55, v55, v4

.La0_pa_1:
	s_waitcnt lgkmcnt(0)
	v_mfma_f32_16x16x32_bf16 v[156:159], v[124:127], v[92:95], v[156:159]
	v_mfma_f32_16x16x32_bf16 v[160:163], v[132:135], v[92:95], v[160:163]
	v_mfma_f32_16x16x32_bf16 v[156:159], v[128:131], v[96:99], v[156:159]
	v_mfma_f32_16x16x32_bf16 v[160:163], v[136:139], v[96:99], v[160:163]
	v_add_f32_e32 v164, 0x41000000, v88
	s_nop 7
	v_max3_f32 v165, v156, v157, v158
	v_max3_f32 v166, v159, v160, v161
	v_max3_f32 v165, v165, v162, v163
	v_max_f32_e32 v165, v165, v166
	v_cmp_gt_f32_e32 vcc, v165, v164
	s_cbranch_vccz .La0_nr_a1_0
	ds_bpermute_b32 v166, v194, v165
	s_waitcnt lgkmcnt(0)
	v_max_f32_e32 v165, v165, v166
	ds_bpermute_b32 v166, v195, v165
	s_waitcnt lgkmcnt(0)
	v_max3_f32 v165, v165, v166, v88
	v_sub_f32_e32 v166, v88, v165
	v_exp_f32_e32 v166, v166
	v_mov_b32_e32 v88, v165
	s_nop 0
	v_mul_f32_e32 v72, v72, v166
	v_mul_f32_e32 v73, v73, v166
	v_mul_f32_e32 v74, v74, v166
	v_mul_f32_e32 v75, v75, v166
	v_mul_f32_e32 v8, v8, v166
	v_mul_f32_e32 v9, v9, v166
	v_mul_f32_e32 v10, v10, v166
	v_mul_f32_e32 v11, v11, v166
	v_mul_f32_e32 v12, v12, v166
	v_mul_f32_e32 v13, v13, v166
	v_mul_f32_e32 v14, v14, v166
	v_mul_f32_e32 v15, v15, v166
	v_mul_f32_e32 v16, v16, v166
	v_mul_f32_e32 v17, v17, v166
	v_mul_f32_e32 v18, v18, v166
	v_mul_f32_e32 v19, v19, v166
	v_mul_f32_e32 v20, v20, v166
	v_mul_f32_e32 v21, v21, v166
	v_mul_f32_e32 v22, v22, v166
	v_mul_f32_e32 v23, v23, v166

.La0_pa_8:
	s_waitcnt lgkmcnt(0)
	v_mfma_f32_16x16x32_bf16 v[198:201], v[124:127], v[116:119], v[198:201]
	v_mfma_f32_16x16x32_bf16 v[202:205], v[132:135], v[116:119], v[202:205]
	v_mfma_f32_16x16x32_bf16 v[198:201], v[128:131], v[120:123], v[198:201]
	v_mfma_f32_16x16x32_bf16 v[202:205], v[136:139], v[120:123], v[202:205]
	v_add_f32_e32 v5, 0x41000000, v91
	s_nop 7
	v_max3_f32 v7, v198, v199, v200
	v_max3_f32 v206, v201, v202, v203
	v_max3_f32 v7, v7, v204, v205
	v_max_f32_e32 v7, v7, v206
	v_cmp_gt_f32_e32 vcc, v7, v5
	s_cbranch_vccz .La0_nr_a8_3
	ds_bpermute_b32 v206, v194, v7
	s_waitcnt lgkmcnt(0)
	v_max_f32_e32 v7, v7, v206
	ds_bpermute_b32 v206, v195, v7
	s_waitcnt lgkmcnt(0)
	v_max3_f32 v7, v7, v206, v91
	v_sub_f32_e32 v206, v91, v7
	v_exp_f32_e32 v206, v206
	v_mov_b32_e32 v91, v7
	s_nop 0
	v_mul_f32_e32 v84, v84, v206
	v_mul_f32_e32 v85, v85, v206
	v_mul_f32_e32 v86, v86, v206
	v_mul_f32_e32 v87, v87, v206
	v_mul_f32_e32 v56, v56, v206
	v_mul_f32_e32 v57, v57, v206
	v_mul_f32_e32 v58, v58, v206
	v_mul_f32_e32 v59, v59, v206
	v_mul_f32_e32 v60, v60, v206
	v_mul_f32_e32 v61, v61, v206
	v_mul_f32_e32 v62, v62, v206
	v_mul_f32_e32 v63, v63, v206
	v_mul_f32_e32 v64, v64, v206
	v_mul_f32_e32 v65, v65, v206
	v_mul_f32_e32 v66, v66, v206
	v_mul_f32_e32 v67, v67, v206
	v_mul_f32_e32 v68, v68, v206
	v_mul_f32_e32 v69, v69, v206
	v_mul_f32_e32 v70, v70, v206
	v_mul_f32_e32 v71, v71, v206

.La0_gateld:
	s_add_i32 s5, s41, s54
	s_add_i32 s5, s5, 4
	s_lshl_b32 s5, s5, 17
	s_add_u32 s0, s56, s5
	s_addc_u32 s1, s57, 0
	global_load_dwordx4 v[124:127], v196, s[0:1] nt
	global_load_dwordx4 v[128:131], v196, s[0:1] offset:16 nt
	s_add_i32 s5, s41, s54
	s_add_i32 s5, s5, 6
	s_lshl_b32 s5, s5, 17
	s_add_u32 s0, s56, s5
	s_addc_u32 s1, s57, 0
	global_load_dwordx4 v[132:135], v196, s[0:1] nt
	global_load_dwordx4 v[136:139], v196, s[0:1] offset:16 nt
.La0_issued:
	s_cmp_eq_u32 s32, 0
	s_cbranch_scc1 .La0_noreq_b
	s_and_b32 s61, s62, 1
	s_lshl_b32 s61, s61, 15
	s_add_i32 s0, s61, 0x4000
	v_add_u32_e32 v209, s0, v190
	ds_read_b128 v[140:143], v209 offset:0
	ds_read_b128 v[144:147], v209 offset:512
	ds_read_b128 v[148:151], v209 offset:1024
	ds_read_b128 v[152:155], v209 offset:1536
	s_add_i32 s60, s60, 1
	s_sub_i32 s0, s60, s41
	s_sub_i32 s0, s0, s54
	s_add_i32 s0, s0, 1
	s_lshl_b32 s0, s0, 11
	v_add_u32_e32 v167, s0, v250
	ds_read_b128 v[156:159], v167 offset:12288
	ds_read_b128 v[160:163], v167 offset:13312
	ds_read_b128 v[232:235], v167 offset:8192
	ds_read_b128 v[236:239], v167 offset:9216
	ds_read_b128 v[180:183], v167 offset:4096
	ds_read_b128 v[184:187], v167 offset:5120
	ds_read_b128 v[198:201], v167 offset:0
	ds_read_b128 v[202:205], v167 offset:1024
.La0_noreq_b:
	s_cmp_eq_u32 s32, 0
	s_cbranch_scc1 .La0_ss_done
	s_cmp_eq_u32 s32, 15
	s_cbranch_scc1 .La0_pb_15
	s_cmp_eq_u32 s32, 7
	s_cbranch_scc1 .La0_pb_7
	s_cmp_eq_u32 s32, 14
	s_cbranch_scc1 .La0_pb_14
	s_cmp_eq_u32 s32, 3
	s_cbranch_scc1 .La0_pb_3
	s_cmp_eq_u32 s32, 12
	s_cbranch_scc1 .La0_pb_12
	s_cmp_eq_u32 s32, 1
	s_cbranch_scc1 .La0_pb_1
	s_cmp_eq_u32 s32, 8
	s_cbranch_scc1 .La0_pb_8
	s_branch .La0_rowdone_b
.La0_pb_15:
	s_waitcnt lgkmcnt(0)
	v_mfma_f32_16x16x32_bf16 v[156:159], v[168:171], v[92:95], v[156:159]
	v_mfma_f32_16x16x32_bf16 v[160:163], v[226:229], v[92:95], v[160:163]
	v_mfma_f32_16x16x32_bf16 v[156:159], v[172:175], v[96:99], v[156:159]
	v_mfma_f32_16x16x32_bf16 v[160:163], v[244:247], v[96:99], v[160:163]
	v_mfma_f32_16x16x32_bf16 v[232:235], v[168:171], v[100:103], v[232:235]
	v_mfma_f32_16x16x32_bf16 v[236:239], v[226:229], v[100:103], v[236:239]
	v_mfma_f32_16x16x32_bf16 v[232:235], v[172:175], v[104:107], v[232:235]
	v_mfma_f32_16x16x32_bf16 v[236:239], v[244:247], v[104:107], v[236:239]
	v_add_f32_e32 v164, 0x41000000, v88
	s_nop 3
	v_max3_f32 v165, v156, v157, v158
	v_max3_f32 v166, v159, v160, v161
	v_max3_f32 v165, v165, v162, v163
	v_max_f32_e32 v165, v165, v166
	v_cmp_gt_f32_e32 vcc, v165, v164
	s_cbranch_vccz .La0_nr_b15_0
	ds_bpermute_b32 v166, v194, v165
	s_waitcnt lgkmcnt(0)
	v_max_f32_e32 v165, v165, v166
	ds_bpermute_b32 v166, v195, v165
	s_waitcnt lgkmcnt(0)
	v_max3_f32 v165, v165, v166, v88
	v_sub_f32_e32 v166, v88, v165
	v_exp_f32_e32 v166, v166
	v_mov_b32_e32 v88, v165
	s_nop 0
	v_mul_f32_e32 v72, v72, v166
	v_mul_f32_e32 v73, v73, v166
	v_mul_f32_e32 v74, v74, v166
	v_mul_f32_e32 v75, v75, v166
	v_mul_f32_e32 v8, v8, v166
	v_mul_f32_e32 v9, v9, v166
	v_mul_f32_e32 v10, v10, v166
	v_mul_f32_e32 v11, v11, v166
	v_mul_f32_e32 v12, v12, v166
	v_mul_f32_e32 v13, v13, v166
	v_mul_f32_e32 v14, v14, v166
	v_mul_f32_e32 v15, v15, v166
	v_mul_f32_e32 v16, v16, v166
	v_mul_f32_e32 v17, v17, v166
	v_mul_f32_e32 v18, v18, v166
	v_mul_f32_e32 v19, v19, v166
	v_mul_f32_e32 v20, v20, v166
	v_mul_f32_e32 v21, v21, v166
	v_mul_f32_e32 v22, v22, v166
	v_mul_f32_e32 v23, v23, v166
.La0_nr_b15_0:
	v_sub_f32_e32 v156, v156, v88
	v_sub_f32_e32 v157, v157, v88
	v_sub_f32_e32 v158, v158, v88
	v_sub_f32_e32 v159, v159, v88
	v_sub_f32_e32 v160, v160, v88
	v_sub_f32_e32 v161, v161, v88
	v_sub_f32_e32 v162, v162, v88
	v_sub_f32_e32 v163, v163, v88
	v_exp_f32_e32 v156, v156
	v_exp_f32_e32 v157, v157
	v_exp_f32_e32 v158, v158
	v_exp_f32_e32 v159, v159
	v_exp_f32_e32 v160, v160
	v_exp_f32_e32 v161, v161
	v_exp_f32_e32 v162, v162
	v_exp_f32_e32 v163, v163
	s_nop 0
	v_cvt_pk_bf16_f32 v156, v156, v157
	v_cvt_pk_bf16_f32 v157, v158, v159
	v_cvt_pk_bf16_f32 v158, v160, v161
	v_cvt_pk_bf16_f32 v159, v162, v163
	v_mfma_f32_16x16x32_bf16 v[180:183], v[168:171], v[108:111], v[180:183]
	v_add_f32_e32 v240, 0x41000000, v89
	v_max3_f32 v241, v232, v233, v234
	v_mfma_f32_16x16x32_bf16 v[184:187], v[226:229], v[108:111], v[184:187]
	v_max3_f32 v242, v235, v236, v237
	v_max3_f32 v241, v241, v238, v239
	v_mfma_f32_16x16x32_bf16 v[180:183], v[172:175], v[112:115], v[180:183]
	v_max_f32_e32 v241, v241, v242
	v_cmp_gt_f32_e32 vcc, v241, v240
	v_mfma_f32_16x16x32_bf16 v[184:187], v[244:247], v[112:115], v[184:187]
	s_cbranch_vccz .La0_nr_b15_1
	ds_bpermute_b32 v242, v194, v241
	s_waitcnt lgkmcnt(0)
	v_max_f32_e32 v241, v241, v242
	ds_bpermute_b32 v242, v195, v241
	s_waitcnt lgkmcnt(0)
	v_max3_f32 v241, v241, v242, v89
	v_sub_f32_e32 v242, v89, v241
	v_exp_f32_e32 v242, v242
	v_mov_b32_e32 v89, v241
	s_nop 0
	v_mul_f32_e32 v76, v76, v242
	v_mul_f32_e32 v77, v77, v242
	v_mul_f32_e32 v78, v78, v242
	v_mul_f32_e32 v79, v79, v242
	v_mul_f32_e32 v24, v24, v242
	v_mul_f32_e32 v25, v25, v242
	v_mul_f32_e32 v26, v26, v242
	v_mul_f32_e32 v27, v27, v242
	v_mul_f32_e32 v28, v28, v242
	v_mul_f32_e32 v29, v29, v242
	v_mul_f32_e32 v30, v30, v242
	v_mul_f32_e32 v31, v31, v242
	v_mul_f32_e32 v32, v32, v242
	v_mul_f32_e32 v33, v33, v242
	v_mul_f32_e32 v34, v34, v242
	v_mul_f32_e32 v35, v35, v242
	v_mul_f32_e32 v36, v36, v242
	v_mul_f32_e32 v37, v37, v242
	v_mul_f32_e32 v38, v38, v242
	v_mul_f32_e32 v39, v39, v242
.La0_nr_b15_1:
	v_mfma_f32_16x16x32_bf16 v[8:11], v[140:143], v[156:159], v[8:11]
	v_sub_f32_e32 v232, v232, v89
	v_sub_f32_e32 v233, v233, v89
	v_sub_f32_e32 v234, v234, v89
	v_sub_f32_e32 v235, v235, v89
	v_mfma_f32_16x16x32_bf16 v[12:15], v[144:147], v[156:159], v[12:15]
	v_sub_f32_e32 v236, v236, v89
	v_sub_f32_e32 v237, v237, v89
	v_sub_f32_e32 v238, v238, v89
	v_sub_f32_e32 v239, v239, v89
	v_mfma_f32_16x16x32_bf16 v[16:19], v[148:151], v[156:159], v[16:19]
	v_exp_f32_e32 v232, v232
	v_exp_f32_e32 v233, v233
	v_exp_f32_e32 v234, v234
	v_exp_f32_e32 v235, v235
	v_mfma_f32_16x16x32_bf16 v[20:23], v[152:155], v[156:159], v[20:23]
	v_exp_f32_e32 v236, v236
	v_exp_f32_e32 v237, v237
	v_exp_f32_e32 v238, v238
	v_exp_f32_e32 v239, v239
	v_mfma_f32_16x16x32_bf16 v[72:75], v[176:179], v[156:159], v[72:75]
	s_nop 0
	v_cvt_pk_bf16_f32 v232, v232, v233
	v_cvt_pk_bf16_f32 v233, v234, v235
	v_cvt_pk_bf16_f32 v234, v236, v237
	v_cvt_pk_bf16_f32 v235, v238, v239
	v_mfma_f32_16x16x32_bf16 v[198:201], v[168:171], v[116:119], v[198:201]
	v_add_f32_e32 v1, 0x41000000, v90
	v_max3_f32 v3, v180, v181, v182
	v_mfma_f32_16x16x32_bf16 v[202:205], v[226:229], v[116:119], v[202:205]
	v_max3_f32 v4, v183, v184, v185
	v_max3_f32 v3, v3, v186, v187
	v_mfma_f32_16x16x32_bf16 v[198:201], v[172:175], v[120:123], v[198:201]
	v_max_f32_e32 v3, v3, v4
	v_cmp_gt_f32_e32 vcc, v3, v1
	v_mfma_f32_16x16x32_bf16 v[202:205], v[244:247], v[120:123], v[202:205]
	s_cbranch_vccz .La0_nr_b15_2
	ds_bpermute_b32 v4, v194, v3
	s_waitcnt lgkmcnt(0)
	v_max_f32_e32 v3, v3, v4
	ds_bpermute_b32 v4, v195, v3
	s_waitcnt lgkmcnt(0)
	v_max3_f32 v3, v3, v4, v90
	v_sub_f32_e32 v4, v90, v3
	v_exp_f32_e32 v4, v4
	v_mov_b32_e32 v90, v3
	s_nop 0
	v_mul_f32_e32 v80, v80, v4
	v_mul_f32_e32 v81, v81, v4
	v_mul_f32_e32 v82, v82, v4
	v_mul_f32_e32 v83, v83, v4
	v_mul_f32_e32 v40, v40, v4
	v_mul_f32_e32 v41, v41, v4
	v_mul_f32_e32 v42, v42, v4
	v_mul_f32_e32 v43, v43, v4
	v_mul_f32_e32 v44, v44, v4
	v_mul_f32_e32 v45, v45, v4
	v_mul_f32_e32 v46, v46, v4
	v_mul_f32_e32 v47, v47, v4
	v_mul_f32_e32 v48, v48, v4
	v_mul_f32_e32 v49, v49, v4
	v_mul_f32_e32 v50, v50, v4
	v_mul_f32_e32 v51, v51, v4
	v_mul_f32_e32 v52, v52, v4
	v_mul_f32_e32 v53, v53, v4
	v_mul_f32_e32 v54, v54, v4
	v_mul_f32_e32 v55, v55, v4

.La0_pb_14:
	s_waitcnt lgkmcnt(0)
	v_mfma_f32_16x16x32_bf16 v[232:235], v[168:171], v[100:103], v[232:235]
	v_mfma_f32_16x16x32_bf16 v[236:239], v[226:229], v[100:103], v[236:239]
	v_mfma_f32_16x16x32_bf16 v[232:235], v[172:175], v[104:107], v[232:235]
	v_mfma_f32_16x16x32_bf16 v[236:239], v[244:247], v[104:107], v[236:239]
	v_mfma_f32_16x16x32_bf16 v[180:183], v[168:171], v[108:111], v[180:183]
	v_mfma_f32_16x16x32_bf16 v[184:187], v[226:229], v[108:111], v[184:187]
	v_mfma_f32_16x16x32_bf16 v[180:183], v[172:175], v[112:115], v[180:183]
	v_mfma_f32_16x16x32_bf16 v[184:187], v[244:247], v[112:115], v[184:187]
	v_add_f32_e32 v240, 0x41000000, v89
	s_nop 3
	v_max3_f32 v241, v232, v233, v234
	v_max3_f32 v242, v235, v236, v237
	v_max3_f32 v241, v241, v238, v239
	v_max_f32_e32 v241, v241, v242
	v_cmp_gt_f32_e32 vcc, v241, v240
	s_cbranch_vccz .La0_nr_b14_1
	ds_bpermute_b32 v242, v194, v241
	s_waitcnt lgkmcnt(0)
	v_max_f32_e32 v241, v241, v242
	ds_bpermute_b32 v242, v195, v241
	s_waitcnt lgkmcnt(0)
	v_max3_f32 v241, v241, v242, v89
	v_sub_f32_e32 v242, v89, v241
	v_exp_f32_e32 v242, v242
	v_mov_b32_e32 v89, v241
	s_nop 0
	v_mul_f32_e32 v76, v76, v242
	v_mul_f32_e32 v77, v77, v242
	v_mul_f32_e32 v78, v78, v242
	v_mul_f32_e32 v79, v79, v242
	v_mul_f32_e32 v24, v24, v242
	v_mul_f32_e32 v25, v25, v242
	v_mul_f32_e32 v26, v26, v242
	v_mul_f32_e32 v27, v27, v242
	v_mul_f32_e32 v28, v28, v242
	v_mul_f32_e32 v29, v29, v242
	v_mul_f32_e32 v30, v30, v242
	v_mul_f32_e32 v31, v31, v242
	v_mul_f32_e32 v32, v32, v242
	v_mul_f32_e32 v33, v33, v242
	v_mul_f32_e32 v34, v34, v242
	v_mul_f32_e32 v35, v35, v242
	v_mul_f32_e32 v36, v36, v242
	v_mul_f32_e32 v37, v37, v242
	v_mul_f32_e32 v38, v38, v242
	v_mul_f32_e32 v39, v39, v242
.La0_nr_b14_1:
	v_sub_f32_e32 v232, v232, v89
	v_sub_f32_e32 v233, v233, v89
	v_sub_f32_e32 v234, v234, v89
	v_sub_f32_e32 v235, v235, v89
	v_sub_f32_e32 v236, v236, v89
	v_sub_f32_e32 v237, v237, v89
	v_sub_f32_e32 v238, v238, v89
	v_sub_f32_e32 v239, v239, v89
	v_exp_f32_e32 v232, v232
	v_exp_f32_e32 v233, v233
	v_exp_f32_e32 v234, v234
	v_exp_f32_e32 v235, v235
	v_exp_f32_e32 v236, v236
	v_exp_f32_e32 v237, v237
	v_exp_f32_e32 v238, v238
	v_exp_f32_e32 v239, v239
	s_nop 0
	v_cvt_pk_bf16_f32 v232, v232, v233
	v_cvt_pk_bf16_f32 v233, v234, v235
	v_cvt_pk_bf16_f32 v234, v236, v237
	v_cvt_pk_bf16_f32 v235, v238, v239
	v_mfma_f32_16x16x32_bf16 v[198:201], v[168:171], v[116:119], v[198:201]
	v_add_f32_e32 v1, 0x41000000, v90
	v_max3_f32 v3, v180, v181, v182
	v_mfma_f32_16x16x32_bf16 v[202:205], v[226:229], v[116:119], v[202:205]
	v_max3_f32 v4, v183, v184, v185
	v_max3_f32 v3, v3, v186, v187
	v_mfma_f32_16x16x32_bf16 v[198:201], v[172:175], v[120:123], v[198:201]
	v_max_f32_e32 v3, v3, v4
	v_cmp_gt_f32_e32 vcc, v3, v1
	v_mfma_f32_16x16x32_bf16 v[202:205], v[244:247], v[120:123], v[202:205]
	s_cbranch_vccz .La0_nr_b14_2
	ds_bpermute_b32 v4, v194, v3
	s_waitcnt lgkmcnt(0)
	v_max_f32_e32 v3, v3, v4
	ds_bpermute_b32 v4, v195, v3
	s_waitcnt lgkmcnt(0)
	v_max3_f32 v3, v3, v4, v90
	v_sub_f32_e32 v4, v90, v3
	v_exp_f32_e32 v4, v4
	v_mov_b32_e32 v90, v3
	s_nop 0
	v_mul_f32_e32 v80, v80, v4
	v_mul_f32_e32 v81, v81, v4
	v_mul_f32_e32 v82, v82, v4
	v_mul_f32_e32 v83, v83, v4
	v_mul_f32_e32 v40, v40, v4
	v_mul_f32_e32 v41, v41, v4
	v_mul_f32_e32 v42, v42, v4
	v_mul_f32_e32 v43, v43, v4
	v_mul_f32_e32 v44, v44, v4
	v_mul_f32_e32 v45, v45, v4
	v_mul_f32_e32 v46, v46, v4
	v_mul_f32_e32 v47, v47, v4
	v_mul_f32_e32 v48, v48, v4
	v_mul_f32_e32 v49, v49, v4
	v_mul_f32_e32 v50, v50, v4
	v_mul_f32_e32 v51, v51, v4
	v_mul_f32_e32 v52, v52, v4
	v_mul_f32_e32 v53, v53, v4
	v_mul_f32_e32 v54, v54, v4
	v_mul_f32_e32 v55, v55, v4

.La0_pb_12:
	s_waitcnt lgkmcnt(0)
	v_mfma_f32_16x16x32_bf16 v[180:183], v[168:171], v[108:111], v[180:183]
	v_mfma_f32_16x16x32_bf16 v[184:187], v[226:229], v[108:111], v[184:187]
	v_mfma_f32_16x16x32_bf16 v[180:183], v[172:175], v[112:115], v[180:183]
	v_mfma_f32_16x16x32_bf16 v[184:187], v[244:247], v[112:115], v[184:187]
	v_mfma_f32_16x16x32_bf16 v[198:201], v[168:171], v[116:119], v[198:201]
	v_mfma_f32_16x16x32_bf16 v[202:205], v[226:229], v[116:119], v[202:205]
	v_mfma_f32_16x16x32_bf16 v[198:201], v[172:175], v[120:123], v[198:201]
	v_mfma_f32_16x16x32_bf16 v[202:205], v[244:247], v[120:123], v[202:205]
	v_add_f32_e32 v1, 0x41000000, v90
	s_nop 3
	v_max3_f32 v3, v180, v181, v182
	v_max3_f32 v4, v183, v184, v185
	v_max3_f32 v3, v3, v186, v187
	v_max_f32_e32 v3, v3, v4
	v_cmp_gt_f32_e32 vcc, v3, v1
	s_cbranch_vccz .La0_nr_b12_2
	ds_bpermute_b32 v4, v194, v3
	s_waitcnt lgkmcnt(0)
	v_max_f32_e32 v3, v3, v4
	ds_bpermute_b32 v4, v195, v3
	s_waitcnt lgkmcnt(0)
	v_max3_f32 v3, v3, v4, v90
	v_sub_f32_e32 v4, v90, v3
	v_exp_f32_e32 v4, v4
	v_mov_b32_e32 v90, v3
	s_nop 0
	v_mul_f32_e32 v80, v80, v4
	v_mul_f32_e32 v81, v81, v4
	v_mul_f32_e32 v82, v82, v4
	v_mul_f32_e32 v83, v83, v4
	v_mul_f32_e32 v40, v40, v4
	v_mul_f32_e32 v41, v41, v4
	v_mul_f32_e32 v42, v42, v4
	v_mul_f32_e32 v43, v43, v4
	v_mul_f32_e32 v44, v44, v4
	v_mul_f32_e32 v45, v45, v4
	v_mul_f32_e32 v46, v46, v4
	v_mul_f32_e32 v47, v47, v4
	v_mul_f32_e32 v48, v48, v4
	v_mul_f32_e32 v49, v49, v4
	v_mul_f32_e32 v50, v50, v4
	v_mul_f32_e32 v51, v51, v4
	v_mul_f32_e32 v52, v52, v4
	v_mul_f32_e32 v53, v53, v4
	v_mul_f32_e32 v54, v54, v4
	v_mul_f32_e32 v55, v55, v4

.La0_pb_1:
	s_waitcnt lgkmcnt(0)
	v_mfma_f32_16x16x32_bf16 v[156:159], v[168:171], v[92:95], v[156:159]
	v_mfma_f32_16x16x32_bf16 v[160:163], v[226:229], v[92:95], v[160:163]
	v_mfma_f32_16x16x32_bf16 v[156:159], v[172:175], v[96:99], v[156:159]
	v_mfma_f32_16x16x32_bf16 v[160:163], v[244:247], v[96:99], v[160:163]
	v_add_f32_e32 v164, 0x41000000, v88
	s_nop 7
	v_max3_f32 v165, v156, v157, v158
	v_max3_f32 v166, v159, v160, v161
	v_max3_f32 v165, v165, v162, v163
	v_max_f32_e32 v165, v165, v166
	v_cmp_gt_f32_e32 vcc, v165, v164
	s_cbranch_vccz .La0_nr_b1_0
	ds_bpermute_b32 v166, v194, v165
	s_waitcnt lgkmcnt(0)
	v_max_f32_e32 v165, v165, v166
	ds_bpermute_b32 v166, v195, v165
	s_waitcnt lgkmcnt(0)
	v_max3_f32 v165, v165, v166, v88
	v_sub_f32_e32 v166, v88, v165
	v_exp_f32_e32 v166, v166
	v_mov_b32_e32 v88, v165
	s_nop 0
	v_mul_f32_e32 v72, v72, v166
	v_mul_f32_e32 v73, v73, v166
	v_mul_f32_e32 v74, v74, v166
	v_mul_f32_e32 v75, v75, v166
	v_mul_f32_e32 v8, v8, v166
	v_mul_f32_e32 v9, v9, v166
	v_mul_f32_e32 v10, v10, v166
	v_mul_f32_e32 v11, v11, v166
	v_mul_f32_e32 v12, v12, v166
	v_mul_f32_e32 v13, v13, v166
	v_mul_f32_e32 v14, v14, v166
	v_mul_f32_e32 v15, v15, v166
	v_mul_f32_e32 v16, v16, v166
	v_mul_f32_e32 v17, v17, v166
	v_mul_f32_e32 v18, v18, v166
	v_mul_f32_e32 v19, v19, v166
	v_mul_f32_e32 v20, v20, v166
	v_mul_f32_e32 v21, v21, v166
	v_mul_f32_e32 v22, v22, v166
	v_mul_f32_e32 v23, v23, v166

.La0_pb_8:
	s_waitcnt lgkmcnt(0)
	v_mfma_f32_16x16x32_bf16 v[198:201], v[168:171], v[116:119], v[198:201]
	v_mfma_f32_16x16x32_bf16 v[202:205], v[226:229], v[116:119], v[202:205]
	v_mfma_f32_16x16x32_bf16 v[198:201], v[172:175], v[120:123], v[198:201]
	v_mfma_f32_16x16x32_bf16 v[202:205], v[244:247], v[120:123], v[202:205]
	v_add_f32_e32 v5, 0x41000000, v91
	s_nop 7
	v_max3_f32 v7, v198, v199, v200
	v_max3_f32 v206, v201, v202, v203
	v_max3_f32 v7, v7, v204, v205
	v_max_f32_e32 v7, v7, v206
	v_cmp_gt_f32_e32 vcc, v7, v5
	s_cbranch_vccz .La0_nr_b8_3
	ds_bpermute_b32 v206, v194, v7
	s_waitcnt lgkmcnt(0)
	v_max_f32_e32 v7, v7, v206
	ds_bpermute_b32 v206, v195, v7
	s_waitcnt lgkmcnt(0)
	v_max3_f32 v7, v7, v206, v91
	v_sub_f32_e32 v206, v91, v7
	v_exp_f32_e32 v206, v206
	v_mov_b32_e32 v91, v7
	s_nop 0
	v_mul_f32_e32 v84, v84, v206
	v_mul_f32_e32 v85, v85, v206
	v_mul_f32_e32 v86, v86, v206
	v_mul_f32_e32 v87, v87, v206
	v_mul_f32_e32 v56, v56, v206
	v_mul_f32_e32 v57, v57, v206
	v_mul_f32_e32 v58, v58, v206
	v_mul_f32_e32 v59, v59, v206
	v_mul_f32_e32 v60, v60, v206
	v_mul_f32_e32 v61, v61, v206
	v_mul_f32_e32 v62, v62, v206
	v_mul_f32_e32 v63, v63, v206
	v_mul_f32_e32 v64, v64, v206
	v_mul_f32_e32 v65, v65, v206
	v_mul_f32_e32 v66, v66, v206
	v_mul_f32_e32 v67, v67, v206
	v_mul_f32_e32 v68, v68, v206
	v_mul_f32_e32 v69, v69, v206
	v_mul_f32_e32 v70, v70, v206
	v_mul_f32_e32 v71, v71, v206

.LBB0_394:
	s_add_u32 s25, s30, 0x100
	s_addc_u32 s48, s31, 0
	v_lshl_add_u64 v[146:147], s[10:11], 0, v[138:139]
	v_lshl_add_u64 v[148:149], s[10:11], 0, v[140:141]
	s_mov_b32 s49, -2
	s_mov_b64 s[30:31], 0
	v_readfirstlane_b32 s98, v0
	s_nop 3
	s_lshr_b32 s98, s98, 8
	s_cmp_eq_u32 s98, 1
	s_cbranch_scc0 .Lprio_g2_done
	s_setprio 1
.Lprio_g2_done:
.LBB0_395:
	v_add_u32_e32 v164, s43, v150
	v_add_u32_e32 v180, s44, v150
	s_add_u32 s36, s10, s30
	ds_read_b128 v[152:155], v164
	ds_read_b128 v[156:159], v164 offset:1024
	ds_read_b128 v[160:163], v164 offset:2048
	ds_read_b128 v[164:167], v164 offset:3072
	ds_read_b128 v[168:171], v180
	ds_read_b128 v[172:175], v180 offset:1024
	ds_read_b128 v[176:179], v180 offset:2048
	ds_read_b128 v[180:183], v180 offset:3072
	s_addc_u32 s37, s11, s31
	s_add_u32 s36, s36, 0x100
	s_addc_u32 s37, s37, 0
	s_add_u32 s50, s25, s30
	s_addc_u32 s51, s48, s31
	s_cmpk_eq_i32 s30, 0x700
	s_cselect_b32 s39, s29, s37
	s_cselect_b32 s38, s28, s36
	s_cselect_b32 s37, s27, s51
	s_cselect_b32 s36, s26, s50
	v_lshl_add_u64 v[192:193], v[146:147], 0, s[30:31]
	s_add_i32 m0, s20, 0xc000
	ds_read_b128 v[184:187], v151
	ds_read_b128 v[188:191], v151 offset:1024
	ds_read_b128 v[196:199], v151 offset:2048
	ds_read_b128 v[200:203], v151 offset:3072
	ds_read_b128 v[204:207], v151 offset:4096
	ds_read_b128 v[208:211], v151 offset:5120
	ds_read_b128 v[212:215], v151 offset:6144
	ds_read_b128 v[216:219], v151 offset:7168
	global_load_lds_dwordx4 v[192:193], off
	v_lshl_add_u64 v[192:193], v[148:149], 0, s[30:31]
	s_add_i32 m0, s20, 0xe000
	s_nop 0
	global_load_lds_dwordx4 v[192:193], off
	s_waitcnt vmcnt(8)
	s_waitcnt lgkmcnt(0)
	s_barrier
	s_waitcnt lgkmcnt(0)
	v_mfma_f32_16x16x32_bf16 v[126:129], v[152:155], v[184:187], v[126:129]
	v_mfma_f32_16x16x32_bf16 v[122:125], v[160:163], v[184:187], v[122:125]
	v_mfma_f32_16x16x32_bf16 v[118:121], v[152:155], v[196:199], v[118:121]
	v_mfma_f32_16x16x32_bf16 v[114:117], v[160:163], v[196:199], v[114:117]
	v_mfma_f32_16x16x32_bf16 v[110:113], v[152:155], v[204:207], v[110:113]
	v_mfma_f32_16x16x32_bf16 v[102:105], v[160:163], v[204:207], v[102:105]
	v_mfma_f32_16x16x32_bf16 v[94:97], v[152:155], v[212:215], v[94:97]
	v_mfma_f32_16x16x32_bf16 v[86:89], v[160:163], v[212:215], v[86:89]
	v_mfma_f32_16x16x32_bf16 v[126:129], v[156:159], v[188:191], v[126:129]
	v_mfma_f32_16x16x32_bf16 v[122:125], v[164:167], v[188:191], v[122:125]
	v_mfma_f32_16x16x32_bf16 v[118:121], v[156:159], v[200:203], v[118:121]
	v_mfma_f32_16x16x32_bf16 v[114:117], v[164:167], v[200:203], v[114:117]
	v_mfma_f32_16x16x32_bf16 v[110:113], v[156:159], v[208:211], v[110:113]
	v_mfma_f32_16x16x32_bf16 v[102:105], v[164:167], v[208:211], v[102:105]
	v_mfma_f32_16x16x32_bf16 v[94:97], v[156:159], v[216:219], v[94:97]
	v_mfma_f32_16x16x32_bf16 v[86:89], v[164:167], v[216:219], v[86:89]
	v_mfma_f32_16x16x32_bf16 v[106:109], v[168:171], v[184:187], v[106:109]
	v_mfma_f32_16x16x32_bf16 v[98:101], v[176:179], v[184:187], v[98:101]
	v_mfma_f32_16x16x32_bf16 v[90:93], v[168:171], v[196:199], v[90:93]
	v_mfma_f32_16x16x32_bf16 v[82:85], v[176:179], v[196:199], v[82:85]
	v_mfma_f32_16x16x32_bf16 v[78:81], v[168:171], v[204:207], v[78:81]
	v_mfma_f32_16x16x32_bf16 v[74:77], v[176:179], v[204:207], v[74:77]
	v_mfma_f32_16x16x32_bf16 v[70:73], v[168:171], v[212:215], v[70:73]
	v_mfma_f32_16x16x32_bf16 v[66:69], v[176:179], v[212:215], v[66:69]
	v_mfma_f32_16x16x32_bf16 v[106:109], v[172:175], v[188:191], v[106:109]
	v_mfma_f32_16x16x32_bf16 v[98:101], v[180:183], v[188:191], v[98:101]
	v_mfma_f32_16x16x32_bf16 v[90:93], v[172:175], v[200:203], v[90:93]
	v_mfma_f32_16x16x32_bf16 v[82:85], v[180:183], v[200:203], v[82:85]
	v_mfma_f32_16x16x32_bf16 v[78:81], v[172:175], v[208:211], v[78:81]
	v_mfma_f32_16x16x32_bf16 v[74:77], v[180:183], v[208:211], v[74:77]
	v_mfma_f32_16x16x32_bf16 v[70:73], v[172:175], v[216:219], v[70:73]
	v_mfma_f32_16x16x32_bf16 v[66:69], v[180:183], v[216:219], v[66:69]
	s_barrier
	s_add_i32 s50, s43, s15
	v_lshl_add_u64 v[192:193], s[36:37], 0, v[130:131]
	s_mov_b32 m0, s50
	ds_read_b128 v[184:187], v151 offset:16384
	ds_read_b128 v[188:191], v151 offset:17408
	ds_read_b128 v[196:199], v151 offset:18432
	ds_read_b128 v[200:203], v151 offset:19456
	ds_read_b128 v[204:207], v151 offset:20480
	ds_read_b128 v[208:211], v151 offset:21504
	ds_read_b128 v[212:215], v151 offset:22528
	ds_read_b128 v[216:219], v151 offset:23552
	global_load_lds_dwordx4 v[192:193], off
	s_add_i32 m0, s50, 0x2000
	s_add_u32 s50, s36, 0x40000
	v_lshl_add_u64 v[220:221], s[36:37], 0, v[132:133]
	s_addc_u32 s51, s37, 0
	s_add_i32 s53, s44, s15
	global_load_lds_dwordx4 v[220:221], off
	v_lshl_add_u64 v[222:223], s[50:51], 0, v[130:131]
	s_mov_b32 m0, s53
	v_lshl_add_u64 v[224:225], s[38:39], 0, v[136:137]
	global_load_lds_dwordx4 v[222:223], off
	v_lshl_add_u64 v[222:223], s[50:51], 0, v[132:133]
	s_add_i32 m0, s53, 0x2000
	s_nop 0
	global_load_lds_dwordx4 v[222:223], off
	v_lshl_add_u64 v[222:223], s[38:39], 0, v[134:135]
	s_mov_b32 m0, s20
	s_nop 0
	global_load_lds_dwordx4 v[222:223], off
	s_mov_b32 m0, s21
	s_nop 0
	global_load_lds_dwordx4 v[224:225], off
	s_waitcnt vmcnt(8)
	s_waitcnt lgkmcnt(0)
	s_barrier
	s_waitcnt lgkmcnt(0)
	v_mfma_f32_16x16x32_bf16 v[62:65], v[152:155], v[184:187], v[62:65]
	v_mfma_f32_16x16x32_bf16 v[58:61], v[160:163], v[184:187], v[58:61]
	v_mfma_f32_16x16x32_bf16 v[54:57], v[152:155], v[196:199], v[54:57]
	v_mfma_f32_16x16x32_bf16 v[50:53], v[160:163], v[196:199], v[50:53]
	v_mfma_f32_16x16x32_bf16 v[46:49], v[152:155], v[204:207], v[46:49]
	v_mfma_f32_16x16x32_bf16 v[38:41], v[160:163], v[204:207], v[38:41]
	v_mfma_f32_16x16x32_bf16 v[30:33], v[152:155], v[212:215], v[30:33]
	v_mfma_f32_16x16x32_bf16 v[22:25], v[160:163], v[212:215], v[22:25]
	v_mfma_f32_16x16x32_bf16 v[62:65], v[156:159], v[188:191], v[62:65]
	v_mfma_f32_16x16x32_bf16 v[58:61], v[164:167], v[188:191], v[58:61]
	v_mfma_f32_16x16x32_bf16 v[54:57], v[156:159], v[200:203], v[54:57]
	v_mfma_f32_16x16x32_bf16 v[50:53], v[164:167], v[200:203], v[50:53]
	v_mfma_f32_16x16x32_bf16 v[46:49], v[156:159], v[208:211], v[46:49]
	v_mfma_f32_16x16x32_bf16 v[38:41], v[164:167], v[208:211], v[38:41]
	v_mfma_f32_16x16x32_bf16 v[30:33], v[156:159], v[216:219], v[30:33]
	v_mfma_f32_16x16x32_bf16 v[22:25], v[164:167], v[216:219], v[22:25]
	v_mfma_f32_16x16x32_bf16 v[42:45], v[168:171], v[184:187], v[42:45]
	v_mfma_f32_16x16x32_bf16 v[34:37], v[176:179], v[184:187], v[34:37]
	v_mfma_f32_16x16x32_bf16 v[26:29], v[168:171], v[196:199], v[26:29]
	v_mfma_f32_16x16x32_bf16 v[18:21], v[176:179], v[196:199], v[18:21]
	v_mfma_f32_16x16x32_bf16 v[14:17], v[168:171], v[204:207], v[14:17]
	v_mfma_f32_16x16x32_bf16 v[10:13], v[176:179], v[204:207], v[10:13]
	v_mfma_f32_16x16x32_bf16 v[6:9], v[168:171], v[212:215], v[6:9]
	v_mfma_f32_16x16x32_bf16 v[2:5], v[176:179], v[212:215], v[2:5]
	v_mfma_f32_16x16x32_bf16 v[42:45], v[172:175], v[188:191], v[42:45]
	v_mfma_f32_16x16x32_bf16 v[34:37], v[180:183], v[188:191], v[34:37]
	v_mfma_f32_16x16x32_bf16 v[26:29], v[172:175], v[200:203], v[26:29]
	v_mfma_f32_16x16x32_bf16 v[18:21], v[180:183], v[200:203], v[18:21]
	v_mfma_f32_16x16x32_bf16 v[14:17], v[172:175], v[208:211], v[14:17]
	v_mfma_f32_16x16x32_bf16 v[10:13], v[180:183], v[208:211], v[10:13]
	v_mfma_f32_16x16x32_bf16 v[6:9], v[172:175], v[216:219], v[6:9]
	v_mfma_f32_16x16x32_bf16 v[2:5], v[180:183], v[216:219], v[2:5]
	s_barrier
	s_add_i32 s50, 0, 0x18000
	s_add_i32 s51, 0, 0x1c000
	v_add_u32_e32 v164, s50, v150
	v_add_u32_e32 v180, s51, v150
	ds_read_b128 v[152:155], v164
	ds_read_b128 v[156:159], v164 offset:1024
	ds_read_b128 v[160:163], v164 offset:2048
	ds_read_b128 v[164:167], v164 offset:3072
	ds_read_b128 v[168:171], v180
	ds_read_b128 v[172:175], v180 offset:1024
	ds_read_b128 v[176:179], v180 offset:2048
	ds_read_b128 v[180:183], v180 offset:3072
	s_add_u32 s38, s38, 0x40000
	s_addc_u32 s39, s39, 0
	s_mov_b32 m0, s34
	v_lshl_add_u64 v[226:227], s[38:39], 0, v[134:135]
	ds_read_b128 v[184:187], v151 offset:32768
	ds_read_b128 v[188:191], v151 offset:33792
	ds_read_b128 v[196:199], v151 offset:34816
	ds_read_b128 v[200:203], v151 offset:35840
	ds_read_b128 v[204:207], v151 offset:36864
	ds_read_b128 v[208:211], v151 offset:37888
	ds_read_b128 v[212:215], v151 offset:38912
	ds_read_b128 v[216:219], v151 offset:39936
	global_load_lds_dwordx4 v[226:227], off
	v_lshl_add_u64 v[226:227], s[38:39], 0, v[136:137]
	s_mov_b32 m0, s35
	s_nop 0
	global_load_lds_dwordx4 v[226:227], off
	s_waitcnt vmcnt(8)
	s_waitcnt lgkmcnt(0)
	s_barrier
	s_waitcnt lgkmcnt(0)
	v_mfma_f32_16x16x32_bf16 v[126:129], v[152:155], v[184:187], v[126:129]
	v_mfma_f32_16x16x32_bf16 v[122:125], v[160:163], v[184:187], v[122:125]
	v_mfma_f32_16x16x32_bf16 v[118:121], v[152:155], v[196:199], v[118:121]
	v_mfma_f32_16x16x32_bf16 v[114:117], v[160:163], v[196:199], v[114:117]
	v_mfma_f32_16x16x32_bf16 v[110:113], v[152:155], v[204:207], v[110:113]
	v_mfma_f32_16x16x32_bf16 v[102:105], v[160:163], v[204:207], v[102:105]
	v_mfma_f32_16x16x32_bf16 v[94:97], v[152:155], v[212:215], v[94:97]
	v_mfma_f32_16x16x32_bf16 v[86:89], v[160:163], v[212:215], v[86:89]
	v_mfma_f32_16x16x32_bf16 v[126:129], v[156:159], v[188:191], v[126:129]
	v_mfma_f32_16x16x32_bf16 v[122:125], v[164:167], v[188:191], v[122:125]
	v_mfma_f32_16x16x32_bf16 v[118:121], v[156:159], v[200:203], v[118:121]
	v_mfma_f32_16x16x32_bf16 v[114:117], v[164:167], v[200:203], v[114:117]
	v_mfma_f32_16x16x32_bf16 v[110:113], v[156:159], v[208:211], v[110:113]
	v_mfma_f32_16x16x32_bf16 v[102:105], v[164:167], v[208:211], v[102:105]
	v_mfma_f32_16x16x32_bf16 v[94:97], v[156:159], v[216:219], v[94:97]
	v_mfma_f32_16x16x32_bf16 v[86:89], v[164:167], v[216:219], v[86:89]
	v_mfma_f32_16x16x32_bf16 v[106:109], v[168:171], v[184:187], v[106:109]
	v_mfma_f32_16x16x32_bf16 v[98:101], v[176:179], v[184:187], v[98:101]
	v_mfma_f32_16x16x32_bf16 v[90:93], v[168:171], v[196:199], v[90:93]
	v_mfma_f32_16x16x32_bf16 v[82:85], v[176:179], v[196:199], v[82:85]
	v_mfma_f32_16x16x32_bf16 v[78:81], v[168:171], v[204:207], v[78:81]
	v_mfma_f32_16x16x32_bf16 v[74:77], v[176:179], v[204:207], v[74:77]
	v_mfma_f32_16x16x32_bf16 v[70:73], v[168:171], v[212:215], v[70:73]
	v_mfma_f32_16x16x32_bf16 v[66:69], v[176:179], v[212:215], v[66:69]
	v_mfma_f32_16x16x32_bf16 v[106:109], v[172:175], v[188:191], v[106:109]
	v_mfma_f32_16x16x32_bf16 v[98:101], v[180:183], v[188:191], v[98:101]
	v_mfma_f32_16x16x32_bf16 v[90:93], v[172:175], v[200:203], v[90:93]
	v_mfma_f32_16x16x32_bf16 v[82:85], v[180:183], v[200:203], v[82:85]
	v_mfma_f32_16x16x32_bf16 v[78:81], v[172:175], v[208:211], v[78:81]
	v_mfma_f32_16x16x32_bf16 v[74:77], v[180:183], v[208:211], v[74:77]
	v_mfma_f32_16x16x32_bf16 v[70:73], v[172:175], v[216:219], v[70:73]
	v_mfma_f32_16x16x32_bf16 v[66:69], v[180:183], v[216:219], v[66:69]
	s_barrier
	s_add_i32 s38, s50, s15
	v_lshl_add_u64 v[192:193], v[192:193], 0, s[22:23]
	s_mov_b32 m0, s38
	ds_read_b128 v[184:187], v151 offset:49152
	ds_read_b128 v[188:191], v151 offset:50176
	ds_read_b128 v[196:199], v151 offset:51200
	ds_read_b128 v[200:203], v151 offset:52224
	ds_read_b128 v[204:207], v151 offset:53248
	ds_read_b128 v[208:211], v151 offset:54272
	ds_read_b128 v[212:215], v151 offset:55296
	ds_read_b128 v[216:219], v151 offset:56320
	global_load_lds_dwordx4 v[192:193], off
	s_add_i32 m0, s38, 0x2000
	s_add_u32 s36, s36, 0x40080
	v_lshl_add_u64 v[192:193], v[220:221], 0, s[22:23]
	s_addc_u32 s37, s37, 0
	s_add_i32 s38, s51, s15
	global_load_lds_dwordx4 v[192:193], off
	v_lshl_add_u64 v[192:193], s[36:37], 0, v[130:131]
	s_mov_b32 m0, s38
	s_nop 0
	global_load_lds_dwordx4 v[192:193], off
	v_lshl_add_u64 v[192:193], s[36:37], 0, v[132:133]
	s_add_i32 m0, s38, 0x2000
	s_nop 0
	global_load_lds_dwordx4 v[192:193], off
	v_lshl_add_u64 v[192:193], v[222:223], 0, s[22:23]
	s_mov_b32 m0, s41
	s_nop 0
	global_load_lds_dwordx4 v[192:193], off
	v_lshl_add_u64 v[192:193], v[224:225], 0, s[22:23]
	s_mov_b32 m0, s42
	s_nop 0
	global_load_lds_dwordx4 v[192:193], off
	s_waitcnt vmcnt(8)
	s_waitcnt lgkmcnt(0)
	s_barrier
	s_waitcnt lgkmcnt(0)
	v_mfma_f32_16x16x32_bf16 v[62:65], v[152:155], v[184:187], v[62:65]
	v_mfma_f32_16x16x32_bf16 v[58:61], v[160:163], v[184:187], v[58:61]
	v_mfma_f32_16x16x32_bf16 v[54:57], v[152:155], v[196:199], v[54:57]
	v_mfma_f32_16x16x32_bf16 v[50:53], v[160:163], v[196:199], v[50:53]
	v_mfma_f32_16x16x32_bf16 v[46:49], v[152:155], v[204:207], v[46:49]
	v_mfma_f32_16x16x32_bf16 v[38:41], v[160:163], v[204:207], v[38:41]
	v_mfma_f32_16x16x32_bf16 v[30:33], v[152:155], v[212:215], v[30:33]
	v_mfma_f32_16x16x32_bf16 v[22:25], v[160:163], v[212:215], v[22:25]
	v_mfma_f32_16x16x32_bf16 v[62:65], v[156:159], v[188:191], v[62:65]
	v_mfma_f32_16x16x32_bf16 v[58:61], v[164:167], v[188:191], v[58:61]
	v_mfma_f32_16x16x32_bf16 v[54:57], v[156:159], v[200:203], v[54:57]
	v_mfma_f32_16x16x32_bf16 v[50:53], v[164:167], v[200:203], v[50:53]
	v_mfma_f32_16x16x32_bf16 v[46:49], v[156:159], v[208:211], v[46:49]
	v_mfma_f32_16x16x32_bf16 v[38:41], v[164:167], v[208:211], v[38:41]
	v_mfma_f32_16x16x32_bf16 v[30:33], v[156:159], v[216:219], v[30:33]
	v_mfma_f32_16x16x32_bf16 v[22:25], v[164:167], v[216:219], v[22:25]
	v_mfma_f32_16x16x32_bf16 v[42:45], v[168:171], v[184:187], v[42:45]
	v_mfma_f32_16x16x32_bf16 v[34:37], v[176:179], v[184:187], v[34:37]
	v_mfma_f32_16x16x32_bf16 v[26:29], v[168:171], v[196:199], v[26:29]
	v_mfma_f32_16x16x32_bf16 v[18:21], v[176:179], v[196:199], v[18:21]
	v_mfma_f32_16x16x32_bf16 v[14:17], v[168:171], v[204:207], v[14:17]
	v_mfma_f32_16x16x32_bf16 v[10:13], v[176:179], v[204:207], v[10:13]
	v_mfma_f32_16x16x32_bf16 v[6:9], v[168:171], v[212:215], v[6:9]
	v_mfma_f32_16x16x32_bf16 v[2:5], v[176:179], v[212:215], v[2:5]
	v_mfma_f32_16x16x32_bf16 v[42:45], v[172:175], v[188:191], v[42:45]
	v_mfma_f32_16x16x32_bf16 v[34:37], v[180:183], v[188:191], v[34:37]
	v_mfma_f32_16x16x32_bf16 v[26:29], v[172:175], v[200:203], v[26:29]
	v_mfma_f32_16x16x32_bf16 v[18:21], v[180:183], v[200:203], v[18:21]
	v_mfma_f32_16x16x32_bf16 v[14:17], v[172:175], v[208:211], v[14:17]
	v_mfma_f32_16x16x32_bf16 v[10:13], v[180:183], v[208:211], v[10:13]
	v_mfma_f32_16x16x32_bf16 v[6:9], v[172:175], v[216:219], v[6:9]
	v_mfma_f32_16x16x32_bf16 v[2:5], v[180:183], v[216:219], v[2:5]
	s_barrier
	s_add_i32 s49, s49, 2
	s_add_u32 s30, s30, 0x100
	s_addc_u32 s31, s31, 0
	s_cmp_gt_u32 s49, 13
	s_cbranch_scc0 .LBB0_395
	s_setprio 0
	s_add_u32 s30, s25, 0xffffff00
	s_addc_u32 s31, s48, -1
	s_andn2_b64 vcc, exec, s[6:7]
	s_cbranch_vccnz .LBB0_386
	v_mov_b32_e32 v2, 0
	s_mov_b32 s8, s45
	s_mov_b32 s0, s24
	s_mov_b64 s[10:11], s[28:29]
	s_mov_b32 s40, s47
	v_mov_b32_e32 v3, v2
	v_mov_b32_e32 v4, v2
	v_mov_b32_e32 v5, v2
	v_mov_b32_e32 v6, v2
	v_mov_b32_e32 v7, v2
	v_mov_b32_e32 v8, v2
	v_mov_b32_e32 v9, v2
	v_mov_b32_e32 v10, v2
	v_mov_b32_e32 v11, v2
	v_mov_b32_e32 v12, v2
	v_mov_b32_e32 v13, v2
	v_mov_b32_e32 v14, v2
	v_mov_b32_e32 v15, v2
	v_mov_b32_e32 v16, v2
	v_mov_b32_e32 v17, v2
	v_mov_b32_e32 v18, v2
	v_mov_b32_e32 v19, v2
	v_mov_b32_e32 v20, v2
	v_mov_b32_e32 v21, v2
	v_mov_b32_e32 v26, v2
	v_mov_b32_e32 v27, v2
	v_mov_b32_e32 v28, v2
	v_mov_b32_e32 v29, v2
	v_mov_b32_e32 v34, v2
	v_mov_b32_e32 v35, v2
	v_mov_b32_e32 v36, v2
	v_mov_b32_e32 v37, v2
	v_mov_b32_e32 v42, v2
	v_mov_b32_e32 v43, v2
	v_mov_b32_e32 v44, v2
	v_mov_b32_e32 v45, v2
	v_mov_b32_e32 v22, v2
	v_mov_b32_e32 v23, v2
	v_mov_b32_e32 v24, v2
	v_mov_b32_e32 v25, v2
	v_mov_b32_e32 v30, v2
	v_mov_b32_e32 v31, v2
	v_mov_b32_e32 v32, v2
	v_mov_b32_e32 v33, v2
	v_mov_b32_e32 v38, v2
	v_mov_b32_e32 v39, v2
	v_mov_b32_e32 v40, v2
	v_mov_b32_e32 v41, v2
	v_mov_b32_e32 v46, v2
	v_mov_b32_e32 v47, v2
	v_mov_b32_e32 v48, v2
	v_mov_b32_e32 v49, v2
	v_mov_b32_e32 v50, v2
	v_mov_b32_e32 v51, v2
	v_mov_b32_e32 v52, v2
	v_mov_b32_e32 v53, v2
	v_mov_b32_e32 v54, v2
	v_mov_b32_e32 v55, v2
	v_mov_b32_e32 v56, v2
	v_mov_b32_e32 v57, v2
	v_mov_b32_e32 v58, v2
	v_mov_b32_e32 v59, v2
	v_mov_b32_e32 v60, v2
	v_mov_b32_e32 v61, v2
	v_mov_b32_e32 v62, v2
	v_mov_b32_e32 v63, v2
	v_mov_b32_e32 v64, v2
	v_mov_b32_e32 v65, v2
	v_mov_b32_e32 v66, v2
	v_mov_b32_e32 v67, v2
	v_mov_b32_e32 v68, v2
	v_mov_b32_e32 v69, v2
	v_mov_b32_e32 v70, v2
	v_mov_b32_e32 v71, v2
	v_mov_b32_e32 v72, v2
	v_mov_b32_e32 v73, v2
	v_mov_b32_e32 v74, v2
	v_mov_b32_e32 v75, v2
	v_mov_b32_e32 v76, v2
	v_mov_b32_e32 v77, v2
	v_mov_b32_e32 v78, v2
	v_mov_b32_e32 v79, v2
	v_mov_b32_e32 v80, v2
	v_mov_b32_e32 v81, v2
	v_mov_b32_e32 v82, v2
	v_mov_b32_e32 v83, v2
	v_mov_b32_e32 v84, v2
	v_mov_b32_e32 v85, v2
	v_mov_b32_e32 v90, v2
	v_mov_b32_e32 v91, v2
	v_mov_b32_e32 v92, v2
	v_mov_b32_e32 v93, v2
	v_mov_b32_e32 v98, v2
	v_mov_b32_e32 v99, v2
	v_mov_b32_e32 v100, v2
	v_mov_b32_e32 v101, v2
	v_mov_b32_e32 v106, v2
	v_mov_b32_e32 v107, v2
	v_mov_b32_e32 v108, v2
	v_mov_b32_e32 v109, v2
	v_mov_b32_e32 v86, v2
	v_mov_b32_e32 v87, v2
	v_mov_b32_e32 v88, v2
	v_mov_b32_e32 v89, v2
	v_mov_b32_e32 v94, v2
	v_mov_b32_e32 v95, v2
	v_mov_b32_e32 v96, v2
	v_mov_b32_e32 v97, v2
	v_mov_b32_e32 v102, v2
	v_mov_b32_e32 v103, v2
	v_mov_b32_e32 v104, v2
	v_mov_b32_e32 v105, v2
	v_mov_b32_e32 v110, v2
	v_mov_b32_e32 v111, v2
	v_mov_b32_e32 v112, v2
	v_mov_b32_e32 v113, v2
	v_mov_b32_e32 v114, v2
	v_mov_b32_e32 v115, v2
	v_mov_b32_e32 v116, v2
	v_mov_b32_e32 v117, v2
	v_mov_b32_e32 v118, v2
	v_mov_b32_e32 v119, v2
	v_mov_b32_e32 v120, v2
	v_mov_b32_e32 v121, v2
	v_mov_b32_e32 v122, v2
	v_mov_b32_e32 v123, v2
	v_mov_b32_e32 v124, v2
	v_mov_b32_e32 v125, v2
	v_mov_b32_e32 v126, v2
	v_mov_b32_e32 v127, v2
	v_mov_b32_e32 v128, v2
	v_mov_b32_e32 v129, v2
	s_andn2_b64 vcc, exec, s[4:5]
	s_cbranch_vccnz .LBB0_387

.LBB0_589:
	s_add_u32 s83, s8, 0x100
	s_mov_b32 s87, s27
	s_addc_u32 s62, s9, 0
	s_lshl_b64 s[90:91], s[26:27], 7
	s_lshl_b64 s[76:77], s[86:87], 7
	v_mad_u64_u32 v[142:143], s[8:9], s26, v1, v[4:5]
	v_mad_u64_u32 v[144:145], s[8:9], s26, v5, v[156:157]
	s_add_u32 s8, s68, s80
	s_addc_u32 s9, s69, s81
	v_mul_lo_u32 v148, s70, v1
	v_mul_lo_u32 v146, s70, v5
	s_add_u32 s8, s8, 0x80
	v_add_u32_e32 v138, v148, v4
	v_add_u32_e32 v140, v146, v156
	v_add_u32_e32 v146, v183, v146
	v_mov_b32_e32 v147, v2
	s_addc_u32 s9, s9, 0
	v_add_u32_e32 v148, v184, v148
	v_mov_b32_e32 v149, v2
	v_mov_b32_e32 v139, v2
	v_mov_b32_e32 v141, v2
	v_mov_b32_e32 v143, v2
	v_mov_b32_e32 v145, v2
	v_lshl_add_u64 v[146:147], s[8:9], 0, v[146:147]
	v_lshl_add_u64 v[148:149], s[8:9], 0, v[148:149]
	s_mov_b32 s63, -2
	s_mov_b64 s[8:9], 0
	v_readfirstlane_b32 s98, v0
	s_nop 3
	s_lshr_b32 s98, s98, 8
	s_cmp_eq_u32 s98, 1
	s_cbranch_scc0 .Lprio_g3_done
	s_setprio 1

.LBB0_590:
	s_add_u32 vcc_lo, s68, s8
	s_addc_u32 vcc_hi, s69, s9
	s_add_u32 vcc_lo, vcc_lo, 0x100
	s_addc_u32 vcc_hi, vcc_hi, 0
	s_and_b64 s[38:39], exec, s[38:39]
	s_cselect_b32 s39, s89, vcc_hi
	s_cselect_b32 s38, s88, vcc_lo
	s_add_i32 s43, 0, 0x10000
	v_add_u32_e32 v168, s43, v179
	s_add_i32 s41, 0, 0x14000
	ds_read_b128 v[160:163], v168
	ds_read_b128 v[164:167], v168 offset:1024
	ds_read_b128 v[186:189], v168 offset:2048
	ds_read_b128 v[190:193], v168 offset:3072
	v_add_u32_e32 v168, s41, v179
	ds_read_b128 v[194:197], v168
	ds_read_b128 v[198:201], v168 offset:1024
	ds_read_b128 v[202:205], v168 offset:2048
	ds_read_b128 v[206:209], v168 offset:3072
	v_lshl_add_u64 v[168:169], v[148:149], 0, s[8:9]
	s_add_i32 m0, s51, 0xc000
	ds_read_b128 v[210:213], v185
	ds_read_b128 v[214:217], v185 offset:1024
	ds_read_b128 v[218:221], v185 offset:2048
	ds_read_b128 v[222:225], v185 offset:3072
	ds_read_b128 v[226:229], v185 offset:4096
	ds_read_b128 v[232:235], v185 offset:5120
	ds_read_b128 v[236:239], v185 offset:6144
	ds_read_b128 v[240:243], v185 offset:7168
	global_load_lds_dwordx4 v[168:169], off
	v_lshl_add_u64 v[168:169], v[146:147], 0, s[8:9]
	s_add_i32 m0, s51, 0xe000
	s_nop 0
	global_load_lds_dwordx4 v[168:169], off
	s_waitcnt vmcnt(8)
	s_waitcnt lgkmcnt(0)
	s_barrier
	s_waitcnt lgkmcnt(0)
	v_mfma_f32_16x16x32_bf16 v[134:137], v[160:163], v[210:213], v[134:137]
	v_mfma_f32_16x16x32_bf16 v[130:133], v[186:189], v[210:213], v[130:133]
	v_mfma_f32_16x16x32_bf16 v[126:129], v[160:163], v[218:221], v[126:129]
	v_mfma_f32_16x16x32_bf16 v[122:125], v[186:189], v[218:221], v[122:125]
	v_mfma_f32_16x16x32_bf16 v[118:121], v[160:163], v[226:229], v[118:121]
	v_mfma_f32_16x16x32_bf16 v[114:117], v[186:189], v[226:229], v[114:117]
	v_mfma_f32_16x16x32_bf16 v[110:113], v[160:163], v[236:239], v[110:113]
	v_mfma_f32_16x16x32_bf16 v[106:109], v[186:189], v[236:239], v[106:109]
	v_mfma_f32_16x16x32_bf16 v[134:137], v[164:167], v[214:217], v[134:137]
	v_mfma_f32_16x16x32_bf16 v[130:133], v[190:193], v[214:217], v[130:133]
	v_mfma_f32_16x16x32_bf16 v[126:129], v[164:167], v[222:225], v[126:129]
	v_mfma_f32_16x16x32_bf16 v[122:125], v[190:193], v[222:225], v[122:125]
	v_mfma_f32_16x16x32_bf16 v[118:121], v[164:167], v[232:235], v[118:121]
	v_mfma_f32_16x16x32_bf16 v[114:117], v[190:193], v[232:235], v[114:117]
	v_mfma_f32_16x16x32_bf16 v[110:113], v[164:167], v[240:243], v[110:113]
	v_mfma_f32_16x16x32_bf16 v[106:109], v[190:193], v[240:243], v[106:109]
	v_mfma_f32_16x16x32_bf16 v[102:105], v[194:197], v[210:213], v[102:105]
	v_mfma_f32_16x16x32_bf16 v[98:101], v[202:205], v[210:213], v[98:101]
	v_mfma_f32_16x16x32_bf16 v[94:97], v[194:197], v[218:221], v[94:97]
	v_mfma_f32_16x16x32_bf16 v[90:93], v[202:205], v[218:221], v[90:93]
	v_mfma_f32_16x16x32_bf16 v[86:89], v[194:197], v[226:229], v[86:89]
	v_mfma_f32_16x16x32_bf16 v[82:85], v[202:205], v[226:229], v[82:85]
	v_mfma_f32_16x16x32_bf16 v[78:81], v[194:197], v[236:239], v[78:81]
	v_mfma_f32_16x16x32_bf16 v[74:77], v[202:205], v[236:239], v[74:77]
	v_mfma_f32_16x16x32_bf16 v[102:105], v[198:201], v[214:217], v[102:105]
	v_mfma_f32_16x16x32_bf16 v[98:101], v[206:209], v[214:217], v[98:101]
	v_mfma_f32_16x16x32_bf16 v[94:97], v[198:201], v[222:225], v[94:97]
	v_mfma_f32_16x16x32_bf16 v[90:93], v[206:209], v[222:225], v[90:93]
	v_mfma_f32_16x16x32_bf16 v[86:89], v[198:201], v[232:235], v[86:89]
	v_mfma_f32_16x16x32_bf16 v[82:85], v[206:209], v[232:235], v[82:85]
	v_mfma_f32_16x16x32_bf16 v[78:81], v[198:201], v[240:243], v[78:81]
	v_mfma_f32_16x16x32_bf16 v[74:77], v[206:209], v[240:243], v[74:77]
	s_barrier
	s_add_i32 s43, s43, s50
	v_mad_u64_u32 v[168:169], vcc, s87, v3, v[4:5]
	s_mov_b32 m0, s43
	ds_read_b128 v[210:213], v185 offset:16384
	ds_read_b128 v[214:217], v185 offset:17408
	ds_read_b128 v[218:221], v185 offset:18432
	ds_read_b128 v[222:225], v185 offset:19456
	ds_read_b128 v[226:229], v185 offset:20480
	ds_read_b128 v[232:235], v185 offset:21504
	ds_read_b128 v[236:239], v185 offset:22528
	ds_read_b128 v[240:243], v185 offset:23552
	global_load_lds_dwordx4 v168, s[96:97]
	s_add_i32 m0, s43, 0x2000
	s_add_u32 s92, s96, s92
	v_mad_u64_u32 v[246:247], vcc, s87, v155, v[156:157]
	s_addc_u32 s93, s97, s93
	s_add_i32 s41, s41, s50
	global_load_lds_dwordx4 v246, s[96:97]
	s_mov_b32 m0, s41
	v_mov_b32_e32 v169, v2
	v_mov_b32_e32 v247, v2
	global_load_lds_dwordx4 v168, s[92:93]
	s_add_i32 m0, s41, 0x2000
	v_lshl_add_u64 v[244:245], s[96:97], 0, v[168:169]
	v_lshl_add_u64 v[248:249], s[96:97], 0, v[246:247]
	v_lshl_add_u64 v[250:251], s[92:93], 0, v[168:169]
	v_lshl_add_u64 v[168:169], s[92:93], 0, v[246:247]
	global_load_lds_dwordx4 v246, s[92:93]
	v_lshl_add_u64 v[246:247], s[38:39], 0, v[152:153]
	s_mov_b32 m0, s51
	v_lshl_add_u64 v[252:253], s[38:39], 0, v[150:151]
	global_load_lds_dwordx4 v[246:247], off
	s_mov_b32 m0, s73
	s_nop 0
	global_load_lds_dwordx4 v[252:253], off
	s_waitcnt vmcnt(8)
	s_waitcnt lgkmcnt(0)
	s_barrier
	s_waitcnt lgkmcnt(0)
	v_mfma_f32_16x16x32_bf16 v[70:73], v[160:163], v[210:213], v[70:73]
	v_mfma_f32_16x16x32_bf16 v[66:69], v[186:189], v[210:213], v[66:69]
	v_mfma_f32_16x16x32_bf16 v[62:65], v[160:163], v[218:221], v[62:65]
	v_mfma_f32_16x16x32_bf16 v[58:61], v[186:189], v[218:221], v[58:61]
	v_mfma_f32_16x16x32_bf16 v[54:57], v[160:163], v[226:229], v[54:57]
	v_mfma_f32_16x16x32_bf16 v[50:53], v[186:189], v[226:229], v[50:53]
	v_mfma_f32_16x16x32_bf16 v[46:49], v[160:163], v[236:239], v[46:49]
	v_mfma_f32_16x16x32_bf16 v[42:45], v[186:189], v[236:239], v[42:45]
	v_mfma_f32_16x16x32_bf16 v[70:73], v[164:167], v[214:217], v[70:73]
	v_mfma_f32_16x16x32_bf16 v[66:69], v[190:193], v[214:217], v[66:69]
	v_mfma_f32_16x16x32_bf16 v[62:65], v[164:167], v[222:225], v[62:65]
	v_mfma_f32_16x16x32_bf16 v[58:61], v[190:193], v[222:225], v[58:61]
	v_mfma_f32_16x16x32_bf16 v[54:57], v[164:167], v[232:235], v[54:57]
	v_mfma_f32_16x16x32_bf16 v[50:53], v[190:193], v[232:235], v[50:53]
	v_mfma_f32_16x16x32_bf16 v[46:49], v[164:167], v[240:243], v[46:49]
	v_mfma_f32_16x16x32_bf16 v[42:45], v[190:193], v[240:243], v[42:45]
	v_mfma_f32_16x16x32_bf16 v[38:41], v[194:197], v[210:213], v[38:41]
	v_mfma_f32_16x16x32_bf16 v[34:37], v[202:205], v[210:213], v[34:37]
	v_mfma_f32_16x16x32_bf16 v[30:33], v[194:197], v[218:221], v[30:33]
	v_mfma_f32_16x16x32_bf16 v[26:29], v[202:205], v[218:221], v[26:29]
	v_mfma_f32_16x16x32_bf16 v[22:25], v[194:197], v[226:229], v[22:25]
	v_mfma_f32_16x16x32_bf16 v[18:21], v[202:205], v[226:229], v[18:21]
	v_mfma_f32_16x16x32_bf16 v[14:17], v[194:197], v[236:239], v[14:17]
	v_mfma_f32_16x16x32_bf16 v[10:13], v[202:205], v[236:239], v[10:13]
	v_mfma_f32_16x16x32_bf16 v[38:41], v[198:201], v[214:217], v[38:41]
	v_mfma_f32_16x16x32_bf16 v[34:37], v[206:209], v[214:217], v[34:37]
	v_mfma_f32_16x16x32_bf16 v[30:33], v[198:201], v[222:225], v[30:33]
	v_mfma_f32_16x16x32_bf16 v[26:29], v[206:209], v[222:225], v[26:29]
	v_mfma_f32_16x16x32_bf16 v[22:25], v[198:201], v[232:235], v[22:25]
	v_mfma_f32_16x16x32_bf16 v[18:21], v[206:209], v[232:235], v[18:21]
	v_mfma_f32_16x16x32_bf16 v[14:17], v[198:201], v[240:243], v[14:17]
	v_mfma_f32_16x16x32_bf16 v[10:13], v[206:209], v[240:243], v[10:13]
	s_barrier
	s_add_i32 s41, 0, 0x18000
	s_add_i32 s43, 0, 0x1c000
	v_add_u32_e32 v190, s41, v179
	v_add_u32_e32 v206, s43, v179
	ds_read_b128 v[160:163], v190
	ds_read_b128 v[164:167], v190 offset:1024
	ds_read_b128 v[186:189], v190 offset:2048
	ds_read_b128 v[190:193], v190 offset:3072
	ds_read_b128 v[194:197], v206
	ds_read_b128 v[198:201], v206 offset:1024
	ds_read_b128 v[202:205], v206 offset:2048
	ds_read_b128 v[206:209], v206 offset:3072
	s_add_u32 s38, s38, s94
	s_addc_u32 s39, s39, s95
	s_mov_b32 m0, s71
	v_lshl_add_u64 v[152:153], s[38:39], 0, v[152:153]
	ds_read_b128 v[210:213], v185 offset:32768
	ds_read_b128 v[214:217], v185 offset:33792
	ds_read_b128 v[218:221], v185 offset:34816
	ds_read_b128 v[222:225], v185 offset:35840
	ds_read_b128 v[226:229], v185 offset:36864
	ds_read_b128 v[232:235], v185 offset:37888
	ds_read_b128 v[236:239], v185 offset:38912
	ds_read_b128 v[240:243], v185 offset:39936
	global_load_lds_dwordx4 v[152:153], off
	v_lshl_add_u64 v[150:151], s[38:39], 0, v[150:151]
	s_mov_b32 m0, s34
	s_nop 0
	global_load_lds_dwordx4 v[150:151], off
	s_waitcnt vmcnt(8)
	s_waitcnt lgkmcnt(0)
	s_barrier
	s_waitcnt lgkmcnt(0)
	v_mfma_f32_16x16x32_bf16 v[134:137], v[160:163], v[210:213], v[134:137]
	v_mfma_f32_16x16x32_bf16 v[130:133], v[186:189], v[210:213], v[130:133]
	v_mfma_f32_16x16x32_bf16 v[126:129], v[160:163], v[218:221], v[126:129]
	v_mfma_f32_16x16x32_bf16 v[122:125], v[186:189], v[218:221], v[122:125]
	v_mfma_f32_16x16x32_bf16 v[118:121], v[160:163], v[226:229], v[118:121]
	v_mfma_f32_16x16x32_bf16 v[114:117], v[186:189], v[226:229], v[114:117]
	v_mfma_f32_16x16x32_bf16 v[110:113], v[160:163], v[236:239], v[110:113]
	v_mfma_f32_16x16x32_bf16 v[106:109], v[186:189], v[236:239], v[106:109]
	v_mfma_f32_16x16x32_bf16 v[134:137], v[164:167], v[214:217], v[134:137]
	v_mfma_f32_16x16x32_bf16 v[130:133], v[190:193], v[214:217], v[130:133]
	v_mfma_f32_16x16x32_bf16 v[126:129], v[164:167], v[222:225], v[126:129]
	v_mfma_f32_16x16x32_bf16 v[122:125], v[190:193], v[222:225], v[122:125]
	v_mfma_f32_16x16x32_bf16 v[118:121], v[164:167], v[232:235], v[118:121]
	v_mfma_f32_16x16x32_bf16 v[114:117], v[190:193], v[232:235], v[114:117]
	v_mfma_f32_16x16x32_bf16 v[110:113], v[164:167], v[240:243], v[110:113]
	v_mfma_f32_16x16x32_bf16 v[106:109], v[190:193], v[240:243], v[106:109]
	v_mfma_f32_16x16x32_bf16 v[102:105], v[194:197], v[210:213], v[102:105]
	v_mfma_f32_16x16x32_bf16 v[98:101], v[202:205], v[210:213], v[98:101]
	v_mfma_f32_16x16x32_bf16 v[94:97], v[194:197], v[218:221], v[94:97]
	v_mfma_f32_16x16x32_bf16 v[90:93], v[202:205], v[218:221], v[90:93]
	v_mfma_f32_16x16x32_bf16 v[86:89], v[194:197], v[226:229], v[86:89]
	v_mfma_f32_16x16x32_bf16 v[82:85], v[202:205], v[226:229], v[82:85]
	v_mfma_f32_16x16x32_bf16 v[78:81], v[194:197], v[236:239], v[78:81]
	v_mfma_f32_16x16x32_bf16 v[74:77], v[202:205], v[236:239], v[74:77]
	v_mfma_f32_16x16x32_bf16 v[102:105], v[198:201], v[214:217], v[102:105]
	v_mfma_f32_16x16x32_bf16 v[98:101], v[206:209], v[214:217], v[98:101]
	v_mfma_f32_16x16x32_bf16 v[94:97], v[198:201], v[222:225], v[94:97]
	v_mfma_f32_16x16x32_bf16 v[90:93], v[206:209], v[222:225], v[90:93]
	v_mfma_f32_16x16x32_bf16 v[86:89], v[198:201], v[232:235], v[86:89]
	v_mfma_f32_16x16x32_bf16 v[82:85], v[206:209], v[232:235], v[82:85]
	v_mfma_f32_16x16x32_bf16 v[78:81], v[198:201], v[240:243], v[78:81]
	v_mfma_f32_16x16x32_bf16 v[74:77], v[206:209], v[240:243], v[74:77]
	s_barrier
	s_add_i32 s38, s41, s50
	v_lshl_add_u64 v[240:241], v[244:245], 0, s[52:53]
	s_mov_b32 m0, s38
	ds_read_b128 v[150:153], v185 offset:49152
	ds_read_b128 v[210:213], v185 offset:50176
	ds_read_b128 v[214:217], v185 offset:51200
	ds_read_b128 v[218:221], v185 offset:52224
	ds_read_b128 v[222:225], v185 offset:53248
	ds_read_b128 v[226:229], v185 offset:54272
	ds_read_b128 v[232:235], v185 offset:55296
	ds_read_b128 v[236:239], v185 offset:56320
	global_load_lds_dwordx4 v[240:241], off
	v_lshl_add_u64 v[240:241], v[248:249], 0, s[52:53]
	s_add_i32 m0, s38, 0x2000
	s_add_i32 s38, s43, s50
	global_load_lds_dwordx4 v[240:241], off
	v_lshl_add_u64 v[240:241], v[250:251], 0, s[52:53]
	s_mov_b32 m0, s38
	v_lshl_add_u64 v[168:169], v[168:169], 0, s[52:53]
	global_load_lds_dwordx4 v[240:241], off
	s_add_i32 m0, s38, 0x2000
	s_nop 0
	global_load_lds_dwordx4 v[168:169], off
	v_lshl_add_u64 v[168:169], v[246:247], 0, s[52:53]
	s_mov_b32 m0, s23
	s_nop 0
	global_load_lds_dwordx4 v[168:169], off
	v_lshl_add_u64 v[168:169], v[252:253], 0, s[52:53]
	s_mov_b32 m0, s28
	s_nop 0
	global_load_lds_dwordx4 v[168:169], off
	s_waitcnt vmcnt(8)
	s_waitcnt lgkmcnt(0)
	s_barrier
	s_waitcnt lgkmcnt(0)
	v_mfma_f32_16x16x32_bf16 v[70:73], v[160:163], v[150:153], v[70:73]
	v_mfma_f32_16x16x32_bf16 v[66:69], v[186:189], v[150:153], v[66:69]
	v_mfma_f32_16x16x32_bf16 v[62:65], v[160:163], v[214:217], v[62:65]
	v_mfma_f32_16x16x32_bf16 v[58:61], v[186:189], v[214:217], v[58:61]
	v_mfma_f32_16x16x32_bf16 v[54:57], v[160:163], v[222:225], v[54:57]
	v_mfma_f32_16x16x32_bf16 v[50:53], v[186:189], v[222:225], v[50:53]
	v_mfma_f32_16x16x32_bf16 v[46:49], v[160:163], v[232:235], v[46:49]
	v_mfma_f32_16x16x32_bf16 v[42:45], v[186:189], v[232:235], v[42:45]
	v_mfma_f32_16x16x32_bf16 v[70:73], v[164:167], v[210:213], v[70:73]
	v_mfma_f32_16x16x32_bf16 v[66:69], v[190:193], v[210:213], v[66:69]
	v_mfma_f32_16x16x32_bf16 v[62:65], v[164:167], v[218:221], v[62:65]
	v_mfma_f32_16x16x32_bf16 v[58:61], v[190:193], v[218:221], v[58:61]
	v_mfma_f32_16x16x32_bf16 v[54:57], v[164:167], v[226:229], v[54:57]
	v_mfma_f32_16x16x32_bf16 v[50:53], v[190:193], v[226:229], v[50:53]
	v_mfma_f32_16x16x32_bf16 v[46:49], v[164:167], v[236:239], v[46:49]
	v_mfma_f32_16x16x32_bf16 v[42:45], v[190:193], v[236:239], v[42:45]
	v_mfma_f32_16x16x32_bf16 v[38:41], v[194:197], v[150:153], v[38:41]
	v_mfma_f32_16x16x32_bf16 v[34:37], v[202:205], v[150:153], v[34:37]
	v_mfma_f32_16x16x32_bf16 v[30:33], v[194:197], v[214:217], v[30:33]
	v_mfma_f32_16x16x32_bf16 v[26:29], v[202:205], v[214:217], v[26:29]
	v_mfma_f32_16x16x32_bf16 v[22:25], v[194:197], v[222:225], v[22:25]
	v_mfma_f32_16x16x32_bf16 v[18:21], v[202:205], v[222:225], v[18:21]
	v_mfma_f32_16x16x32_bf16 v[14:17], v[194:197], v[232:235], v[14:17]
	v_mfma_f32_16x16x32_bf16 v[10:13], v[202:205], v[232:235], v[10:13]
	v_mfma_f32_16x16x32_bf16 v[38:41], v[198:201], v[210:213], v[38:41]
	v_mfma_f32_16x16x32_bf16 v[34:37], v[206:209], v[210:213], v[34:37]
	v_mfma_f32_16x16x32_bf16 v[30:33], v[198:201], v[218:221], v[30:33]
	v_mfma_f32_16x16x32_bf16 v[26:29], v[206:209], v[218:221], v[26:29]
	v_mfma_f32_16x16x32_bf16 v[22:25], v[198:201], v[226:229], v[22:25]
	v_mfma_f32_16x16x32_bf16 v[18:21], v[206:209], v[226:229], v[18:21]
	v_mfma_f32_16x16x32_bf16 v[14:17], v[198:201], v[236:239], v[14:17]
	v_mfma_f32_16x16x32_bf16 v[10:13], v[206:209], v[236:239], v[10:13]
	s_barrier
	s_add_i32 s63, s63, 2
	s_add_u32 s8, s8, 0x100
	s_addc_u32 s9, s9, 0
	s_cmp_gt_u32 s63, 13
	s_cbranch_scc1 .LBB0_593

.LBB0_593:
	s_setprio 0
	s_and_b64 vcc, exec, s[78:79]
	s_cbranch_vccz .LBB0_595
	s_barrier

.LBB0_945:
	s_add_u32 s13, s22, 0x100
	s_addc_u32 s48, s23, 0
	v_lshl_add_u64 v[146:147], s[8:9], 0, v[138:139]
	v_lshl_add_u64 v[148:149], s[8:9], 0, v[140:141]
	s_mov_b32 s49, -2
	s_mov_b64 s[22:23], 0
	v_readfirstlane_b32 s98, v0
	s_nop 3
	s_lshr_b32 s98, s98, 8
	s_cmp_eq_u32 s98, 1
	s_cbranch_scc0 .Lprio_g4_done
	s_setprio 1
.Lprio_g4_done:
.LBB0_946:
	v_add_u32_e32 v164, s88, v150
	v_add_u32_e32 v180, s45, v150
	s_add_u32 s24, s8, s22
	ds_read_b128 v[152:155], v164
	ds_read_b128 v[156:159], v164 offset:1024
	ds_read_b128 v[160:163], v164 offset:2048
	ds_read_b128 v[164:167], v164 offset:3072
	ds_read_b128 v[168:171], v180
	ds_read_b128 v[172:175], v180 offset:1024
	ds_read_b128 v[176:179], v180 offset:2048
	ds_read_b128 v[180:183], v180 offset:3072
	s_addc_u32 s25, s9, s23
	s_add_u32 s24, s24, 0x100
	s_addc_u32 s25, s25, 0
	s_add_u32 s50, s13, s22
	s_addc_u32 s51, s48, s23
	s_cmpk_eq_i32 s22, 0x700
	s_cselect_b32 s27, s21, s25
	s_cselect_b32 s26, s20, s24
	s_cselect_b32 s25, s17, s51
	s_cselect_b32 s24, s16, s50
	v_lshl_add_u64 v[218:219], v[146:147], 0, s[22:23]
	s_add_i32 m0, s37, 0xc000
	ds_read_b128 v[184:187], v151
	ds_read_b128 v[190:193], v151 offset:1024
	ds_read_b128 v[194:197], v151 offset:2048
	ds_read_b128 v[198:201], v151 offset:3072
	ds_read_b128 v[202:205], v151 offset:4096
	ds_read_b128 v[206:209], v151 offset:5120
	ds_read_b128 v[210:213], v151 offset:6144
	ds_read_b128 v[214:217], v151 offset:7168
	global_load_lds_dwordx4 v[218:219], off
	v_lshl_add_u64 v[218:219], v[148:149], 0, s[22:23]
	s_add_i32 m0, s37, 0xe000
	s_nop 0
	global_load_lds_dwordx4 v[218:219], off
	s_waitcnt vmcnt(8)
	s_waitcnt lgkmcnt(0)
	s_barrier
	s_waitcnt lgkmcnt(0)
	v_mfma_f32_16x16x32_bf16 v[126:129], v[152:155], v[184:187], v[126:129]
	v_mfma_f32_16x16x32_bf16 v[122:125], v[160:163], v[184:187], v[122:125]
	v_mfma_f32_16x16x32_bf16 v[110:113], v[152:155], v[194:197], v[110:113]
	v_mfma_f32_16x16x32_bf16 v[106:109], v[160:163], v[194:197], v[106:109]
	v_mfma_f32_16x16x32_bf16 v[94:97], v[152:155], v[202:205], v[94:97]
	v_mfma_f32_16x16x32_bf16 v[90:93], v[160:163], v[202:205], v[90:93]
	v_mfma_f32_16x16x32_bf16 v[78:81], v[152:155], v[210:213], v[78:81]
	v_mfma_f32_16x16x32_bf16 v[74:77], v[160:163], v[210:213], v[74:77]
	v_mfma_f32_16x16x32_bf16 v[126:129], v[156:159], v[190:193], v[126:129]
	v_mfma_f32_16x16x32_bf16 v[122:125], v[164:167], v[190:193], v[122:125]
	v_mfma_f32_16x16x32_bf16 v[110:113], v[156:159], v[198:201], v[110:113]
	v_mfma_f32_16x16x32_bf16 v[106:109], v[164:167], v[198:201], v[106:109]
	v_mfma_f32_16x16x32_bf16 v[94:97], v[156:159], v[206:209], v[94:97]
	v_mfma_f32_16x16x32_bf16 v[90:93], v[164:167], v[206:209], v[90:93]
	v_mfma_f32_16x16x32_bf16 v[78:81], v[156:159], v[214:217], v[78:81]
	v_mfma_f32_16x16x32_bf16 v[74:77], v[164:167], v[214:217], v[74:77]
	v_mfma_f32_16x16x32_bf16 v[118:121], v[168:171], v[184:187], v[118:121]
	v_mfma_f32_16x16x32_bf16 v[114:117], v[176:179], v[184:187], v[114:117]
	v_mfma_f32_16x16x32_bf16 v[102:105], v[168:171], v[194:197], v[102:105]
	v_mfma_f32_16x16x32_bf16 v[98:101], v[176:179], v[194:197], v[98:101]
	v_mfma_f32_16x16x32_bf16 v[86:89], v[168:171], v[202:205], v[86:89]
	v_mfma_f32_16x16x32_bf16 v[82:85], v[176:179], v[202:205], v[82:85]
	v_mfma_f32_16x16x32_bf16 v[70:73], v[168:171], v[210:213], v[70:73]
	v_mfma_f32_16x16x32_bf16 v[66:69], v[176:179], v[210:213], v[66:69]
	v_mfma_f32_16x16x32_bf16 v[118:121], v[172:175], v[190:193], v[118:121]
	v_mfma_f32_16x16x32_bf16 v[114:117], v[180:183], v[190:193], v[114:117]
	v_mfma_f32_16x16x32_bf16 v[102:105], v[172:175], v[198:201], v[102:105]
	v_mfma_f32_16x16x32_bf16 v[98:101], v[180:183], v[198:201], v[98:101]
	v_mfma_f32_16x16x32_bf16 v[86:89], v[172:175], v[206:209], v[86:89]
	v_mfma_f32_16x16x32_bf16 v[82:85], v[180:183], v[206:209], v[82:85]
	v_mfma_f32_16x16x32_bf16 v[70:73], v[172:175], v[214:217], v[70:73]
	v_mfma_f32_16x16x32_bf16 v[66:69], v[180:183], v[214:217], v[66:69]
	s_barrier
	s_add_i32 s50, s88, s36
	v_lshl_add_u64 v[218:219], s[24:25], 0, v[130:131]
	s_mov_b32 m0, s50
	ds_read_b128 v[184:187], v151 offset:16384
	ds_read_b128 v[190:193], v151 offset:17408
	ds_read_b128 v[194:197], v151 offset:18432
	ds_read_b128 v[198:201], v151 offset:19456
	ds_read_b128 v[202:205], v151 offset:20480
	ds_read_b128 v[206:209], v151 offset:21504
	ds_read_b128 v[210:213], v151 offset:22528
	ds_read_b128 v[214:217], v151 offset:23552
	global_load_lds_dwordx4 v[218:219], off
	s_add_i32 m0, s50, 0x2000
	s_add_u32 s50, s24, 0x40000
	v_lshl_add_u64 v[220:221], s[24:25], 0, v[132:133]
	s_addc_u32 s51, s25, 0
	s_add_i32 s52, s45, s36
	global_load_lds_dwordx4 v[220:221], off
	v_lshl_add_u64 v[222:223], s[50:51], 0, v[130:131]
	s_mov_b32 m0, s52
	v_lshl_add_u64 v[224:225], s[26:27], 0, v[136:137]
	global_load_lds_dwordx4 v[222:223], off
	v_lshl_add_u64 v[222:223], s[50:51], 0, v[132:133]
	s_add_i32 m0, s52, 0x2000
	s_nop 0
	global_load_lds_dwordx4 v[222:223], off
	v_lshl_add_u64 v[222:223], s[26:27], 0, v[134:135]
	s_mov_b32 m0, s37
	s_nop 0
	global_load_lds_dwordx4 v[222:223], off
	s_mov_b32 m0, s38
	s_nop 0
	global_load_lds_dwordx4 v[224:225], off
	s_waitcnt vmcnt(8)
	s_waitcnt lgkmcnt(0)
	s_barrier
	s_waitcnt lgkmcnt(0)
	v_mfma_f32_16x16x32_bf16 v[62:65], v[152:155], v[184:187], v[62:65]
	v_mfma_f32_16x16x32_bf16 v[58:61], v[160:163], v[184:187], v[58:61]
	v_mfma_f32_16x16x32_bf16 v[46:49], v[152:155], v[194:197], v[46:49]
	v_mfma_f32_16x16x32_bf16 v[42:45], v[160:163], v[194:197], v[42:45]
	v_mfma_f32_16x16x32_bf16 v[30:33], v[152:155], v[202:205], v[30:33]
	v_mfma_f32_16x16x32_bf16 v[26:29], v[160:163], v[202:205], v[26:29]
	v_mfma_f32_16x16x32_bf16 v[14:17], v[152:155], v[210:213], v[14:17]
	v_mfma_f32_16x16x32_bf16 v[10:13], v[160:163], v[210:213], v[10:13]
	v_mfma_f32_16x16x32_bf16 v[62:65], v[156:159], v[190:193], v[62:65]
	v_mfma_f32_16x16x32_bf16 v[58:61], v[164:167], v[190:193], v[58:61]
	v_mfma_f32_16x16x32_bf16 v[46:49], v[156:159], v[198:201], v[46:49]
	v_mfma_f32_16x16x32_bf16 v[42:45], v[164:167], v[198:201], v[42:45]
	v_mfma_f32_16x16x32_bf16 v[30:33], v[156:159], v[206:209], v[30:33]
	v_mfma_f32_16x16x32_bf16 v[26:29], v[164:167], v[206:209], v[26:29]
	v_mfma_f32_16x16x32_bf16 v[14:17], v[156:159], v[214:217], v[14:17]
	v_mfma_f32_16x16x32_bf16 v[10:13], v[164:167], v[214:217], v[10:13]
	v_mfma_f32_16x16x32_bf16 v[54:57], v[168:171], v[184:187], v[54:57]
	v_mfma_f32_16x16x32_bf16 v[50:53], v[176:179], v[184:187], v[50:53]
	v_mfma_f32_16x16x32_bf16 v[38:41], v[168:171], v[194:197], v[38:41]
	v_mfma_f32_16x16x32_bf16 v[34:37], v[176:179], v[194:197], v[34:37]
	v_mfma_f32_16x16x32_bf16 v[22:25], v[168:171], v[202:205], v[22:25]
	v_mfma_f32_16x16x32_bf16 v[18:21], v[176:179], v[202:205], v[18:21]
	v_mfma_f32_16x16x32_bf16 v[6:9], v[168:171], v[210:213], v[6:9]
	v_mfma_f32_16x16x32_bf16 v[2:5], v[176:179], v[210:213], v[2:5]
	v_mfma_f32_16x16x32_bf16 v[54:57], v[172:175], v[190:193], v[54:57]
	v_mfma_f32_16x16x32_bf16 v[50:53], v[180:183], v[190:193], v[50:53]
	v_mfma_f32_16x16x32_bf16 v[38:41], v[172:175], v[198:201], v[38:41]
	v_mfma_f32_16x16x32_bf16 v[34:37], v[180:183], v[198:201], v[34:37]
	v_mfma_f32_16x16x32_bf16 v[22:25], v[172:175], v[206:209], v[22:25]
	v_mfma_f32_16x16x32_bf16 v[18:21], v[180:183], v[206:209], v[18:21]
	v_mfma_f32_16x16x32_bf16 v[6:9], v[172:175], v[214:217], v[6:9]
	v_mfma_f32_16x16x32_bf16 v[2:5], v[180:183], v[214:217], v[2:5]
	s_barrier
	s_add_i32 s50, 0, 0x18000
	s_add_i32 s51, 0, 0x1c000
	v_add_u32_e32 v164, s50, v150
	v_add_u32_e32 v180, s51, v150
	ds_read_b128 v[152:155], v164
	ds_read_b128 v[156:159], v164 offset:1024
	ds_read_b128 v[160:163], v164 offset:2048
	ds_read_b128 v[164:167], v164 offset:3072
	ds_read_b128 v[168:171], v180
	ds_read_b128 v[172:175], v180 offset:1024
	ds_read_b128 v[176:179], v180 offset:2048
	ds_read_b128 v[180:183], v180 offset:3072
	s_add_u32 s26, s26, 0x40000
	s_addc_u32 s27, s27, 0
	s_mov_b32 m0, s39
	v_lshl_add_u64 v[226:227], s[26:27], 0, v[134:135]
	ds_read_b128 v[184:187], v151 offset:32768
	ds_read_b128 v[190:193], v151 offset:33792
	ds_read_b128 v[194:197], v151 offset:34816
	ds_read_b128 v[198:201], v151 offset:35840
	ds_read_b128 v[202:205], v151 offset:36864
	ds_read_b128 v[206:209], v151 offset:37888
	ds_read_b128 v[210:213], v151 offset:38912
	ds_read_b128 v[214:217], v151 offset:39936
	global_load_lds_dwordx4 v[226:227], off
	v_lshl_add_u64 v[226:227], s[26:27], 0, v[136:137]
	s_mov_b32 m0, s41
	s_nop 0
	global_load_lds_dwordx4 v[226:227], off
	s_waitcnt vmcnt(8)
	s_waitcnt lgkmcnt(0)
	s_barrier
	s_waitcnt lgkmcnt(0)
	v_mfma_f32_16x16x32_bf16 v[126:129], v[152:155], v[184:187], v[126:129]
	v_mfma_f32_16x16x32_bf16 v[122:125], v[160:163], v[184:187], v[122:125]
	v_mfma_f32_16x16x32_bf16 v[110:113], v[152:155], v[194:197], v[110:113]
	v_mfma_f32_16x16x32_bf16 v[106:109], v[160:163], v[194:197], v[106:109]
	v_mfma_f32_16x16x32_bf16 v[94:97], v[152:155], v[202:205], v[94:97]
	v_mfma_f32_16x16x32_bf16 v[90:93], v[160:163], v[202:205], v[90:93]
	v_mfma_f32_16x16x32_bf16 v[78:81], v[152:155], v[210:213], v[78:81]
	v_mfma_f32_16x16x32_bf16 v[74:77], v[160:163], v[210:213], v[74:77]
	v_mfma_f32_16x16x32_bf16 v[126:129], v[156:159], v[190:193], v[126:129]
	v_mfma_f32_16x16x32_bf16 v[122:125], v[164:167], v[190:193], v[122:125]
	v_mfma_f32_16x16x32_bf16 v[110:113], v[156:159], v[198:201], v[110:113]
	v_mfma_f32_16x16x32_bf16 v[106:109], v[164:167], v[198:201], v[106:109]
	v_mfma_f32_16x16x32_bf16 v[94:97], v[156:159], v[206:209], v[94:97]
	v_mfma_f32_16x16x32_bf16 v[90:93], v[164:167], v[206:209], v[90:93]
	v_mfma_f32_16x16x32_bf16 v[78:81], v[156:159], v[214:217], v[78:81]
	v_mfma_f32_16x16x32_bf16 v[74:77], v[164:167], v[214:217], v[74:77]
	v_mfma_f32_16x16x32_bf16 v[118:121], v[168:171], v[184:187], v[118:121]
	v_mfma_f32_16x16x32_bf16 v[114:117], v[176:179], v[184:187], v[114:117]
	v_mfma_f32_16x16x32_bf16 v[102:105], v[168:171], v[194:197], v[102:105]
	v_mfma_f32_16x16x32_bf16 v[98:101], v[176:179], v[194:197], v[98:101]
	v_mfma_f32_16x16x32_bf16 v[86:89], v[168:171], v[202:205], v[86:89]
	v_mfma_f32_16x16x32_bf16 v[82:85], v[176:179], v[202:205], v[82:85]
	v_mfma_f32_16x16x32_bf16 v[70:73], v[168:171], v[210:213], v[70:73]
	v_mfma_f32_16x16x32_bf16 v[66:69], v[176:179], v[210:213], v[66:69]
	v_mfma_f32_16x16x32_bf16 v[118:121], v[172:175], v[190:193], v[118:121]
	v_mfma_f32_16x16x32_bf16 v[114:117], v[180:183], v[190:193], v[114:117]
	v_mfma_f32_16x16x32_bf16 v[102:105], v[172:175], v[198:201], v[102:105]
	v_mfma_f32_16x16x32_bf16 v[98:101], v[180:183], v[198:201], v[98:101]
	v_mfma_f32_16x16x32_bf16 v[86:89], v[172:175], v[206:209], v[86:89]
	v_mfma_f32_16x16x32_bf16 v[82:85], v[180:183], v[206:209], v[82:85]
	v_mfma_f32_16x16x32_bf16 v[70:73], v[172:175], v[214:217], v[70:73]
	v_mfma_f32_16x16x32_bf16 v[66:69], v[180:183], v[214:217], v[66:69]
	s_barrier
	s_add_i32 s26, s50, s36
	v_lshl_add_u64 v[218:219], v[218:219], 0, s[10:11]
	s_mov_b32 m0, s26
	ds_read_b128 v[184:187], v151 offset:49152
	ds_read_b128 v[190:193], v151 offset:50176
	ds_read_b128 v[194:197], v151 offset:51200
	ds_read_b128 v[198:201], v151 offset:52224
	ds_read_b128 v[202:205], v151 offset:53248
	ds_read_b128 v[206:209], v151 offset:54272
	ds_read_b128 v[210:213], v151 offset:55296
	ds_read_b128 v[214:217], v151 offset:56320
	global_load_lds_dwordx4 v[218:219], off
	s_add_i32 m0, s26, 0x2000
	s_add_u32 s24, s24, 0x40080
	v_lshl_add_u64 v[218:219], v[220:221], 0, s[10:11]
	s_addc_u32 s25, s25, 0
	s_add_i32 s26, s51, s36
	global_load_lds_dwordx4 v[218:219], off
	v_lshl_add_u64 v[218:219], s[24:25], 0, v[130:131]
	s_mov_b32 m0, s26
	s_nop 0
	global_load_lds_dwordx4 v[218:219], off
	v_lshl_add_u64 v[218:219], s[24:25], 0, v[132:133]
	s_add_i32 m0, s26, 0x2000
	s_nop 0
	global_load_lds_dwordx4 v[218:219], off
	v_lshl_add_u64 v[218:219], v[222:223], 0, s[10:11]
	s_mov_b32 m0, s42
	s_nop 0
	global_load_lds_dwordx4 v[218:219], off
	v_lshl_add_u64 v[218:219], v[224:225], 0, s[10:11]
	s_mov_b32 m0, s43
	s_nop 0
	global_load_lds_dwordx4 v[218:219], off
	s_waitcnt vmcnt(8)
	s_waitcnt lgkmcnt(0)
	s_barrier
	s_waitcnt lgkmcnt(0)
	v_mfma_f32_16x16x32_bf16 v[62:65], v[152:155], v[184:187], v[62:65]
	v_mfma_f32_16x16x32_bf16 v[58:61], v[160:163], v[184:187], v[58:61]
	v_mfma_f32_16x16x32_bf16 v[46:49], v[152:155], v[194:197], v[46:49]
	v_mfma_f32_16x16x32_bf16 v[42:45], v[160:163], v[194:197], v[42:45]
	v_mfma_f32_16x16x32_bf16 v[30:33], v[152:155], v[202:205], v[30:33]
	v_mfma_f32_16x16x32_bf16 v[26:29], v[160:163], v[202:205], v[26:29]
	v_mfma_f32_16x16x32_bf16 v[14:17], v[152:155], v[210:213], v[14:17]
	v_mfma_f32_16x16x32_bf16 v[10:13], v[160:163], v[210:213], v[10:13]
	v_mfma_f32_16x16x32_bf16 v[62:65], v[156:159], v[190:193], v[62:65]
	v_mfma_f32_16x16x32_bf16 v[58:61], v[164:167], v[190:193], v[58:61]
	v_mfma_f32_16x16x32_bf16 v[46:49], v[156:159], v[198:201], v[46:49]
	v_mfma_f32_16x16x32_bf16 v[42:45], v[164:167], v[198:201], v[42:45]
	v_mfma_f32_16x16x32_bf16 v[30:33], v[156:159], v[206:209], v[30:33]
	v_mfma_f32_16x16x32_bf16 v[26:29], v[164:167], v[206:209], v[26:29]
	v_mfma_f32_16x16x32_bf16 v[14:17], v[156:159], v[214:217], v[14:17]
	v_mfma_f32_16x16x32_bf16 v[10:13], v[164:167], v[214:217], v[10:13]
	v_mfma_f32_16x16x32_bf16 v[54:57], v[168:171], v[184:187], v[54:57]
	v_mfma_f32_16x16x32_bf16 v[50:53], v[176:179], v[184:187], v[50:53]
	v_mfma_f32_16x16x32_bf16 v[38:41], v[168:171], v[194:197], v[38:41]
	v_mfma_f32_16x16x32_bf16 v[34:37], v[176:179], v[194:197], v[34:37]
	v_mfma_f32_16x16x32_bf16 v[22:25], v[168:171], v[202:205], v[22:25]
	v_mfma_f32_16x16x32_bf16 v[18:21], v[176:179], v[202:205], v[18:21]
	v_mfma_f32_16x16x32_bf16 v[6:9], v[168:171], v[210:213], v[6:9]
	v_mfma_f32_16x16x32_bf16 v[2:5], v[176:179], v[210:213], v[2:5]
	v_mfma_f32_16x16x32_bf16 v[54:57], v[172:175], v[190:193], v[54:57]
	v_mfma_f32_16x16x32_bf16 v[50:53], v[180:183], v[190:193], v[50:53]
	v_mfma_f32_16x16x32_bf16 v[38:41], v[172:175], v[198:201], v[38:41]
	v_mfma_f32_16x16x32_bf16 v[34:37], v[180:183], v[198:201], v[34:37]
	v_mfma_f32_16x16x32_bf16 v[22:25], v[172:175], v[206:209], v[22:25]
	v_mfma_f32_16x16x32_bf16 v[18:21], v[180:183], v[206:209], v[18:21]
	v_mfma_f32_16x16x32_bf16 v[6:9], v[172:175], v[214:217], v[6:9]
	v_mfma_f32_16x16x32_bf16 v[2:5], v[180:183], v[214:217], v[2:5]
	s_barrier
	s_add_i32 s49, s49, 2
	s_add_u32 s22, s22, 0x100
	s_addc_u32 s23, s23, 0
	s_cmp_gt_u32 s49, 13
	s_cbranch_scc0 .LBB0_946
	s_setprio 0
	s_add_u32 s22, s13, 0xffffff00
	s_addc_u32 s23, s48, -1
	s_andn2_b64 vcc, exec, s[4:5]
	s_cbranch_vccnz .LBB0_937
	v_mov_b32_e32 v2, 0
	s_mov_b32 s18, s46
	s_mov_b32 s6, s12
	s_mov_b64 s[8:9], s[20:21]
	s_mov_b32 s44, s47
	v_mov_b32_e32 v3, v2
	v_mov_b32_e32 v4, v2
	v_mov_b32_e32 v5, v2
	v_mov_b32_e32 v6, v2
	v_mov_b32_e32 v7, v2
	v_mov_b32_e32 v8, v2
	v_mov_b32_e32 v9, v2
	v_mov_b32_e32 v18, v2
	v_mov_b32_e32 v19, v2
	v_mov_b32_e32 v20, v2
	v_mov_b32_e32 v21, v2
	v_mov_b32_e32 v22, v2
	v_mov_b32_e32 v23, v2
	v_mov_b32_e32 v24, v2
	v_mov_b32_e32 v25, v2
	v_mov_b32_e32 v34, v2
	v_mov_b32_e32 v35, v2
	v_mov_b32_e32 v36, v2
	v_mov_b32_e32 v37, v2
	v_mov_b32_e32 v38, v2
	v_mov_b32_e32 v39, v2
	v_mov_b32_e32 v40, v2
	v_mov_b32_e32 v41, v2
	v_mov_b32_e32 v50, v2
	v_mov_b32_e32 v51, v2
	v_mov_b32_e32 v52, v2
	v_mov_b32_e32 v53, v2
	v_mov_b32_e32 v54, v2
	v_mov_b32_e32 v55, v2
	v_mov_b32_e32 v56, v2
	v_mov_b32_e32 v57, v2
	v_mov_b32_e32 v10, v2
	v_mov_b32_e32 v11, v2
	v_mov_b32_e32 v12, v2
	v_mov_b32_e32 v13, v2
	v_mov_b32_e32 v14, v2
	v_mov_b32_e32 v15, v2
	v_mov_b32_e32 v16, v2
	v_mov_b32_e32 v17, v2
	v_mov_b32_e32 v26, v2
	v_mov_b32_e32 v27, v2
	v_mov_b32_e32 v28, v2
	v_mov_b32_e32 v29, v2
	v_mov_b32_e32 v30, v2
	v_mov_b32_e32 v31, v2
	v_mov_b32_e32 v32, v2
	v_mov_b32_e32 v33, v2
	v_mov_b32_e32 v42, v2
	v_mov_b32_e32 v43, v2
	v_mov_b32_e32 v44, v2
	v_mov_b32_e32 v45, v2
	v_mov_b32_e32 v46, v2
	v_mov_b32_e32 v47, v2
	v_mov_b32_e32 v48, v2
	v_mov_b32_e32 v49, v2
	v_mov_b32_e32 v58, v2
	v_mov_b32_e32 v59, v2
	v_mov_b32_e32 v60, v2
	v_mov_b32_e32 v61, v2
	v_mov_b32_e32 v62, v2
	v_mov_b32_e32 v63, v2
	v_mov_b32_e32 v64, v2
	v_mov_b32_e32 v65, v2
	v_mov_b32_e32 v66, v2
	v_mov_b32_e32 v67, v2
	v_mov_b32_e32 v68, v2
	v_mov_b32_e32 v69, v2
	v_mov_b32_e32 v70, v2
	v_mov_b32_e32 v71, v2
	v_mov_b32_e32 v72, v2
	v_mov_b32_e32 v73, v2
	v_mov_b32_e32 v82, v2
	v_mov_b32_e32 v83, v2
	v_mov_b32_e32 v84, v2
	v_mov_b32_e32 v85, v2
	v_mov_b32_e32 v86, v2
	v_mov_b32_e32 v87, v2
	v_mov_b32_e32 v88, v2
	v_mov_b32_e32 v89, v2
	v_mov_b32_e32 v98, v2
	v_mov_b32_e32 v99, v2
	v_mov_b32_e32 v100, v2
	v_mov_b32_e32 v101, v2
	v_mov_b32_e32 v102, v2
	v_mov_b32_e32 v103, v2
	v_mov_b32_e32 v104, v2
	v_mov_b32_e32 v105, v2
	v_mov_b32_e32 v114, v2
	v_mov_b32_e32 v115, v2
	v_mov_b32_e32 v116, v2
	v_mov_b32_e32 v117, v2
	v_mov_b32_e32 v118, v2
	v_mov_b32_e32 v119, v2
	v_mov_b32_e32 v120, v2
	v_mov_b32_e32 v121, v2
	v_mov_b32_e32 v74, v2
	v_mov_b32_e32 v75, v2
	v_mov_b32_e32 v76, v2
	v_mov_b32_e32 v77, v2
	v_mov_b32_e32 v78, v2
	v_mov_b32_e32 v79, v2
	v_mov_b32_e32 v80, v2
	v_mov_b32_e32 v81, v2
	v_mov_b32_e32 v90, v2
	v_mov_b32_e32 v91, v2
	v_mov_b32_e32 v92, v2
	v_mov_b32_e32 v93, v2
	v_mov_b32_e32 v94, v2
	v_mov_b32_e32 v95, v2
	v_mov_b32_e32 v96, v2
	v_mov_b32_e32 v97, v2
	v_mov_b32_e32 v106, v2
	v_mov_b32_e32 v107, v2
	v_mov_b32_e32 v108, v2
	v_mov_b32_e32 v109, v2
	v_mov_b32_e32 v110, v2
	v_mov_b32_e32 v111, v2
	v_mov_b32_e32 v112, v2
	v_mov_b32_e32 v113, v2
	v_mov_b32_e32 v122, v2
	v_mov_b32_e32 v123, v2
	v_mov_b32_e32 v124, v2
	v_mov_b32_e32 v125, v2
	v_mov_b32_e32 v126, v2
	v_mov_b32_e32 v127, v2
	v_mov_b32_e32 v128, v2
	v_mov_b32_e32 v129, v2
	s_andn2_b64 vcc, exec, s[0:1]
	s_cbranch_vccnz .LBB0_938
